# v12: v8 with packed v_pk_fma_f32 in the P11 epilogues (same arithmetic order)
# baseline (speedup 1.0000x reference)
; #define LAS __attribute__((address_space(3)))
; DI void indexer_tile(const LAS unsigned char* buf, const f16x8 (&af)[2][8], const f32x4 (&wv)[2][4], float* sc0, float* sc1, int kt, int r32, int h2) {
;     typedef float f32x2_t __attribute__((ext_vector_type(2)));
;     f16x8 bfr[2][8];
; #pragma unroll
;     for (int sub = 0; sub < 2; ++sub)
; #pragma unroll
;         for (int ks = 0; ks < 8; ++ks) bfr[sub][ks] = *(const LAS f16x8*)(buf + (32 * sub + r32) * KT_ROWB + (16 * ks + 8 * h2) * 2);
;     __builtin_amdgcn_sched_barrier(0);
; #pragma unroll
;     for (int sub = 0; sub < 2; ++sub) {
;         f32x16 c0, c1;
; #pragma unroll
;         for (int i = 0; i < 16; ++i) { c0[i] = 0.f; c1[i] = 0.f; }
; #pragma unroll
;         for (int ks = 0; ks < 8; ++ks) { c0 = __builtin_amdgcn_mfma_f32_32x32x16_f16(af[0][ks], bfr[sub][ks], c0, 0, 0, 0); c1 = __builtin_amdgcn_mfma_f32_32x32x16_f16(af[1][ks], bfr[sub][ks], c1, 0, 0, 0); }
;         f32x2_t a0 = {0.f, 0.f}, a1 = {0.f, 0.f};
; #pragma unroll
;         for (int q = 0; q < 4; ++q)
; #pragma unroll
;             for (int e = 0; e < 4; e += 2) {
;                 const f32x2_t r0 = {relu1(c0[4 * q + e]), relu1(c0[4 * q + e + 1])};
;                 const f32x2_t r1 = {relu1(c1[4 * q + e]), relu1(c1[4 * q + e + 1])};
;                 const f32x2_t w0 = {wv[0][q][e], wv[0][q][e + 1]}, w1 = {wv[1][q][e], wv[1][q][e + 1]};
;                 a0 = __builtin_elementwise_fma(r0, w0, a0); a1 = __builtin_elementwise_fma(r1, w1, a1); }
;         float s0 = a0.x + a0.y, s1 = a1.x + a1.y;
;         s0 += __shfl_xor(s0, 32); s1 += __shfl_xor(s1, 32);
;         if (h2 == 0) { sc0[kt * 64 + 32 * sub + r32] = s0; sc1[kt * 64 + 32 * sub + r32] = s1; }
;     }
.LBB0_1827:
	ds_read_b128 v[0:3], v207
	ds_read_b128 v[210:213], v207 offset:32
	ds_read_b128 v[214:217], v207 offset:64
	ds_read_b128 v[218:221], v207 offset:96
	ds_read_b128 v[222:225], v207 offset:128
	ds_read_b128 v[226:229], v207 offset:160
	ds_read_b128 v[230:233], v207 offset:192
	ds_read_b128 v[234:237], v207 offset:224
	ds_read_b128 v[176:179], v207 offset:8704
	ds_read_b128 v[172:175], v207 offset:8736
	ds_read_b128 v[168:171], v207 offset:8768
	ds_read_b128 v[164:167], v207 offset:8800
	ds_read_b128 v[160:163], v207 offset:8832
	ds_read_b128 v[156:159], v207 offset:8864
	ds_read_b128 v[152:155], v207 offset:8896
	ds_read_b128 v[148:151], v207 offset:8928
	s_waitcnt lgkmcnt(15)
	v_mfma_f32_32x32x16_f16 v[16:31], v[36:39], v[0:3], 0
	s_waitcnt lgkmcnt(14)
	v_mfma_f32_32x32x16_f16 v[16:31], v[40:43], v[210:213], v[16:31]
	s_waitcnt lgkmcnt(13)
	v_mfma_f32_32x32x16_f16 v[16:31], v[44:47], v[214:217], v[16:31]
	s_waitcnt lgkmcnt(12)
	v_mfma_f32_32x32x16_f16 v[16:31], v[48:51], v[218:221], v[16:31]
	s_waitcnt lgkmcnt(11)
	v_mfma_f32_32x32x16_f16 v[16:31], v[52:55], v[222:225], v[16:31]
	s_waitcnt lgkmcnt(10)
	v_mfma_f32_32x32x16_f16 v[16:31], v[56:59], v[226:229], v[16:31]
	s_waitcnt lgkmcnt(9)
	v_mfma_f32_32x32x16_f16 v[16:31], v[60:63], v[230:233], v[16:31]
	s_waitcnt lgkmcnt(8)
	v_mfma_f32_32x32x16_f16 v[16:31], v[64:67], v[234:237], v[16:31]
	v_mfma_f32_32x32x16_f16 v[0:15], v[84:87], v[0:3], 0
	v_mfma_f32_32x32x16_f16 v[0:15], v[88:91], v[210:213], v[0:15]
	v_mfma_f32_32x32x16_f16 v[0:15], v[92:95], v[214:217], v[0:15]
	s_nop 8
	v_max_i32_e32 v16, 0, v16
	v_max_i32_e32 v17, 0, v17
	v_pk_fma_f32 v[238:239], v[16:17], v[68:69], 0 op_sel_hi:[1,1,0]
	v_max_i32_e32 v18, 0, v18
	v_max_i32_e32 v19, 0, v19
	v_mfma_f32_32x32x16_f16 v[0:15], v[96:99], v[218:221], v[0:15]
	v_pk_fma_f32 v[238:239], v[18:19], v[70:71], v[238:239]
	v_max_i32_e32 v20, 0, v20
	v_max_i32_e32 v21, 0, v21
	v_pk_fma_f32 v[238:239], v[20:21], v[72:73], v[238:239]
	v_max_i32_e32 v22, 0, v22
	v_mfma_f32_32x32x16_f16 v[0:15], v[100:103], v[222:225], v[0:15]
	v_max_i32_e32 v23, 0, v23
	v_pk_fma_f32 v[238:239], v[22:23], v[74:75], v[238:239]
	v_max_i32_e32 v24, 0, v24
	v_max_i32_e32 v25, 0, v25
	v_pk_fma_f32 v[238:239], v[24:25], v[76:77], v[238:239]
	v_mfma_f32_32x32x16_f16 v[0:15], v[104:107], v[226:229], v[0:15]
	v_max_i32_e32 v26, 0, v26
	v_max_i32_e32 v27, 0, v27
	v_pk_fma_f32 v[238:239], v[26:27], v[78:79], v[238:239]
	v_max_i32_e32 v28, 0, v28
	v_max_i32_e32 v29, 0, v29
	v_mfma_f32_32x32x16_f16 v[0:15], v[108:111], v[230:233], v[0:15]
	v_pk_fma_f32 v[238:239], v[28:29], v[80:81], v[238:239]
	v_max_i32_e32 v30, 0, v30
	v_max_i32_e32 v31, 0, v31
	v_pk_fma_f32 v[238:239], v[30:31], v[82:83], v[238:239]
	v_mfma_f32_32x32x16_f16 v[0:15], v[112:115], v[234:237], v[0:15]
	v_add_f32_e32 v240, v238, v239
	v_mov_b32_e32 v241, v240
	v_lshlrev_b32_e32 v242, 2, v32
	s_nop 0
	v_permlane32_swap_b32_e32 v241, v240
	v_add_f32_e32 v241, v241, v240
	s_mov_b64 exec, s[4:5]
	global_store_dword v242, v241, s[18:19]
	s_mov_b64 exec, -1
	s_waitcnt lgkmcnt(0)
; DI void indexer_tile(const LAS unsigned char* buf, const f16x8 (&af)[2][8], const f32x4 (&wv)[2][4], float* sc0, float* sc1, int kt, int r32, int h2) {
;     ...
;     for (int sub = 0; sub < 2; ++sub) {
;         f32x16 c0, c1;
; #pragma unroll
;         for (int i = 0; i < 16; ++i) { c0[i] = 0.f; c1[i] = 0.f; }
; #pragma unroll
;         for (int ks = 0; ks < 8; ++ks) { c0 = __builtin_amdgcn_mfma_f32_32x32x16_f16(af[0][ks], bfr[sub][ks], c0, 0, 0, 0); c1 = __builtin_amdgcn_mfma_f32_32x32x16_f16(af[1][ks], bfr[sub][ks], c1, 0, 0, 0); }
;         f32x2_t a0 = {0.f, 0.f}, a1 = {0.f, 0.f};
; #pragma unroll
;         for (int q = 0; q < 4; ++q)
; #pragma unroll
;             for (int e = 0; e < 4; e += 2) {
;                 const f32x2_t r0 = {relu1(c0[4 * q + e]), relu1(c0[4 * q + e + 1])};
;                 const f32x2_t r1 = {relu1(c1[4 * q + e]), relu1(c1[4 * q + e + 1])};
;                 const f32x2_t w0 = {wv[0][q][e], wv[0][q][e + 1]}, w1 = {wv[1][q][e], wv[1][q][e + 1]};
;                 a0 = __builtin_elementwise_fma(r0, w0, a0); a1 = __builtin_elementwise_fma(r1, w1, a1); }
;         float s0 = a0.x + a0.y, s1 = a1.x + a1.y;
;         s0 += __shfl_xor(s0, 32); s1 += __shfl_xor(s1, 32);
;         if (h2 == 0) { sc0[kt * 64 + 32 * sub + r32] = s0; sc1[kt * 64 + 32 * sub + r32] = s1; }
;     }
	v_mfma_f32_32x32x16_f16 v[16:31], v[36:39], v[176:179], 0
	v_mfma_f32_32x32x16_f16 v[16:31], v[40:43], v[172:175], v[16:31]
	v_mfma_f32_32x32x16_f16 v[16:31], v[44:47], v[168:171], v[16:31]
	s_nop 8
	v_max_i32_e32 v0, 0, v0
	v_max_i32_e32 v1, 0, v1
	v_pk_fma_f32 v[244:245], v[0:1], v[116:117], 0 op_sel_hi:[1,1,0]
	v_max_i32_e32 v2, 0, v2
	v_max_i32_e32 v3, 0, v3
	v_mfma_f32_32x32x16_f16 v[16:31], v[48:51], v[164:167], v[16:31]
	v_pk_fma_f32 v[244:245], v[2:3], v[118:119], v[244:245]
	v_max_i32_e32 v4, 0, v4
	v_max_i32_e32 v5, 0, v5
	v_pk_fma_f32 v[244:245], v[4:5], v[120:121], v[244:245]
	v_max_i32_e32 v6, 0, v6
	v_mfma_f32_32x32x16_f16 v[16:31], v[52:55], v[160:163], v[16:31]
	v_max_i32_e32 v7, 0, v7
	v_pk_fma_f32 v[244:245], v[6:7], v[122:123], v[244:245]
	v_max_i32_e32 v8, 0, v8
	v_max_i32_e32 v9, 0, v9
	v_pk_fma_f32 v[244:245], v[8:9], v[124:125], v[244:245]
	v_mfma_f32_32x32x16_f16 v[16:31], v[56:59], v[156:159], v[16:31]
	v_max_i32_e32 v10, 0, v10
	v_max_i32_e32 v11, 0, v11
	v_pk_fma_f32 v[244:245], v[10:11], v[126:127], v[244:245]
	v_max_i32_e32 v12, 0, v12
	v_max_i32_e32 v13, 0, v13
	v_mfma_f32_32x32x16_f16 v[16:31], v[60:63], v[152:155], v[16:31]
	v_pk_fma_f32 v[244:245], v[12:13], v[128:129], v[244:245]
	v_max_i32_e32 v14, 0, v14
	v_max_i32_e32 v15, 0, v15
	v_pk_fma_f32 v[244:245], v[14:15], v[130:131], v[244:245]
	v_mfma_f32_32x32x16_f16 v[16:31], v[64:67], v[148:151], v[16:31]
	v_add_f32_e32 v246, v244, v245
	v_mov_b32_e32 v247, v246
	v_lshlrev_b32_e32 v248, 2, v32
	s_nop 0
	v_permlane32_swap_b32_e32 v247, v246
	v_add_f32_e32 v247, v247, v246
	s_mov_b64 exec, s[4:5]
	global_store_dword v248, v247, s[20:21]
	s_mov_b64 exec, -1
	v_mfma_f32_32x32x16_f16 v[0:15], v[84:87], v[176:179], 0
	v_mfma_f32_32x32x16_f16 v[0:15], v[88:91], v[172:175], v[0:15]
	v_mfma_f32_32x32x16_f16 v[0:15], v[92:95], v[168:171], v[0:15]
	s_nop 8
	v_max_i32_e32 v16, 0, v16
	v_max_i32_e32 v17, 0, v17
	v_pk_fma_f32 v[238:239], v[16:17], v[68:69], 0 op_sel_hi:[1,1,0]
	v_max_i32_e32 v18, 0, v18
	v_max_i32_e32 v19, 0, v19
	v_mfma_f32_32x32x16_f16 v[0:15], v[96:99], v[164:167], v[0:15]
	v_pk_fma_f32 v[238:239], v[18:19], v[70:71], v[238:239]
	v_max_i32_e32 v20, 0, v20
	v_max_i32_e32 v21, 0, v21
	v_pk_fma_f32 v[238:239], v[20:21], v[72:73], v[238:239]
	v_max_i32_e32 v22, 0, v22
	v_mfma_f32_32x32x16_f16 v[0:15], v[100:103], v[160:163], v[0:15]
	v_max_i32_e32 v23, 0, v23
	v_pk_fma_f32 v[238:239], v[22:23], v[74:75], v[238:239]
	v_max_i32_e32 v24, 0, v24
	v_max_i32_e32 v25, 0, v25
	v_pk_fma_f32 v[238:239], v[24:25], v[76:77], v[238:239]
	v_mfma_f32_32x32x16_f16 v[0:15], v[104:107], v[156:159], v[0:15]
	v_max_i32_e32 v26, 0, v26
	v_max_i32_e32 v27, 0, v27
	v_pk_fma_f32 v[238:239], v[26:27], v[78:79], v[238:239]
	v_max_i32_e32 v28, 0, v28
	v_max_i32_e32 v29, 0, v29
	v_mfma_f32_32x32x16_f16 v[0:15], v[108:111], v[152:155], v[0:15]
	v_pk_fma_f32 v[238:239], v[28:29], v[80:81], v[238:239]
	v_max_i32_e32 v30, 0, v30
	v_max_i32_e32 v31, 0, v31
	v_pk_fma_f32 v[238:239], v[30:31], v[82:83], v[238:239]
	v_mfma_f32_32x32x16_f16 v[0:15], v[112:115], v[148:151], v[0:15]
	v_add_f32_e32 v240, v238, v239
	v_mov_b32_e32 v241, v240
	v_lshlrev_b32_e32 v242, 2, v32
	s_nop 0
	v_permlane32_swap_b32_e32 v241, v240
	v_add_f32_e32 v241, v241, v240
	s_mov_b64 exec, s[4:5]
	global_store_dword v242, v241, s[18:19] offset:128
	s_mov_b64 exec, -1
	s_nop 11
	v_max_i32_e32 v0, 0, v0
	v_max_i32_e32 v1, 0, v1
	v_pk_fma_f32 v[244:245], v[0:1], v[116:117], 0 op_sel_hi:[1,1,0]
	v_max_i32_e32 v2, 0, v2
	v_max_i32_e32 v3, 0, v3
	v_pk_fma_f32 v[244:245], v[2:3], v[118:119], v[244:245]
	v_max_i32_e32 v4, 0, v4
	v_max_i32_e32 v5, 0, v5
	v_pk_fma_f32 v[244:245], v[4:5], v[120:121], v[244:245]
	v_max_i32_e32 v6, 0, v6
	v_max_i32_e32 v7, 0, v7
	v_pk_fma_f32 v[244:245], v[6:7], v[122:123], v[244:245]
	v_max_i32_e32 v8, 0, v8
	v_max_i32_e32 v9, 0, v9
	v_pk_fma_f32 v[244:245], v[8:9], v[124:125], v[244:245]
	v_max_i32_e32 v10, 0, v10
	v_max_i32_e32 v11, 0, v11
	v_pk_fma_f32 v[244:245], v[10:11], v[126:127], v[244:245]
	v_max_i32_e32 v12, 0, v12
	v_max_i32_e32 v13, 0, v13
	v_pk_fma_f32 v[244:245], v[12:13], v[128:129], v[244:245]
	v_max_i32_e32 v14, 0, v14
	v_max_i32_e32 v15, 0, v15
	v_pk_fma_f32 v[244:245], v[14:15], v[130:131], v[244:245]
	v_add_f32_e32 v246, v244, v245
	v_mov_b32_e32 v247, v246
	v_lshlrev_b32_e32 v248, 2, v32
	s_nop 0
	v_permlane32_swap_b32_e32 v247, v246
	v_add_f32_e32 v247, v247, v246
	s_mov_b64 exec, s[4:5]
	global_store_dword v248, v247, s[20:21] offset:128
	s_mov_b64 exec, -1
	s_add_i32 s27, s11, -3
	s_cmp_lt_i32 s27, s41
	s_cselect_b64 s[24:25], -1, 0
	s_cmp_ge_i32 s27, s41
	s_cbranch_scc1 .LBB0_1833
	s_waitcnt vmcnt(8)
	ds_write_b128 v209, v[140:143] offset:17408
	ds_write_b128 v209, v[144:147] offset:26112

; #define LAS __attribute__((address_space(3)))
; DI void indexer_tile(const LAS unsigned char* buf, const f16x8 (&af)[2][8], const f32x4 (&wv)[2][4], float* sc0, float* sc1, int kt, int r32, int h2) {
;     ...
;     f16x8 bfr[2][8];
; #pragma unroll
;     for (int sub = 0; sub < 2; ++sub)
; #pragma unroll
;         for (int ks = 0; ks < 8; ++ks) bfr[sub][ks] = *(const LAS f16x8*)(buf + (32 * sub + r32) * KT_ROWB + (16 * ks + 8 * h2) * 2);
;     __builtin_amdgcn_sched_barrier(0);
; #pragma unroll
;     for (int sub = 0; sub < 2; ++sub) {
;         f32x16 c0, c1;
; #pragma unroll
;         for (int i = 0; i < 16; ++i) { c0[i] = 0.f; c1[i] = 0.f; }
; #pragma unroll
;         for (int ks = 0; ks < 8; ++ks) { c0 = __builtin_amdgcn_mfma_f32_32x32x16_f16(af[0][ks], bfr[sub][ks], c0, 0, 0, 0); c1 = __builtin_amdgcn_mfma_f32_32x32x16_f16(af[1][ks], bfr[sub][ks], c1, 0, 0, 0); }
;         f32x2_t a0 = {0.f, 0.f}, a1 = {0.f, 0.f};
; #pragma unroll
;         for (int q = 0; q < 4; ++q)
; #pragma unroll
;             for (int e = 0; e < 4; e += 2) {
;                 const f32x2_t r0 = {relu1(c0[4 * q + e]), relu1(c0[4 * q + e + 1])};
;                 const f32x2_t r1 = {relu1(c1[4 * q + e]), relu1(c1[4 * q + e + 1])};
;                 const f32x2_t w0 = {wv[0][q][e], wv[0][q][e + 1]}, w1 = {wv[1][q][e], wv[1][q][e + 1]};
;                 a0 = __builtin_elementwise_fma(r0, w0, a0); a1 = __builtin_elementwise_fma(r1, w1, a1); }
;         float s0 = a0.x + a0.y, s1 = a1.x + a1.y;
;         s0 += __shfl_xor(s0, 32); s1 += __shfl_xor(s1, 32);
;         if (h2 == 0) { sc0[kt * 64 + 32 * sub + r32] = s0; sc1[kt * 64 + 32 * sub + r32] = s1; }
;     }
.LBB0_1836:
	ds_read_b128 v[0:3], v207 offset:17408
	ds_read_b128 v[210:213], v207 offset:17440
	ds_read_b128 v[214:217], v207 offset:17472
	ds_read_b128 v[218:221], v207 offset:17504
	ds_read_b128 v[222:225], v207 offset:17536
	ds_read_b128 v[226:229], v207 offset:17568
	ds_read_b128 v[230:233], v207 offset:17600
	ds_read_b128 v[234:237], v207 offset:17632
	ds_read_b128 v[176:179], v207 offset:26112
	ds_read_b128 v[172:175], v207 offset:26144
	ds_read_b128 v[168:171], v207 offset:26176
	ds_read_b128 v[164:167], v207 offset:26208
	ds_read_b128 v[160:163], v207 offset:26240
	ds_read_b128 v[156:159], v207 offset:26272
	ds_read_b128 v[152:155], v207 offset:26304
	ds_read_b128 v[148:151], v207 offset:26336
	s_waitcnt lgkmcnt(15)
	v_mfma_f32_32x32x16_f16 v[16:31], v[36:39], v[0:3], 0
	s_waitcnt lgkmcnt(14)
	v_mfma_f32_32x32x16_f16 v[16:31], v[40:43], v[210:213], v[16:31]
	s_waitcnt lgkmcnt(13)
	v_mfma_f32_32x32x16_f16 v[16:31], v[44:47], v[214:217], v[16:31]
	s_waitcnt lgkmcnt(12)
	v_mfma_f32_32x32x16_f16 v[16:31], v[48:51], v[218:221], v[16:31]
	s_waitcnt lgkmcnt(11)
	v_mfma_f32_32x32x16_f16 v[16:31], v[52:55], v[222:225], v[16:31]
	s_waitcnt lgkmcnt(10)
	v_mfma_f32_32x32x16_f16 v[16:31], v[56:59], v[226:229], v[16:31]
	s_waitcnt lgkmcnt(9)
	v_mfma_f32_32x32x16_f16 v[16:31], v[60:63], v[230:233], v[16:31]
	s_waitcnt lgkmcnt(8)
	v_mfma_f32_32x32x16_f16 v[16:31], v[64:67], v[234:237], v[16:31]
	v_mfma_f32_32x32x16_f16 v[0:15], v[84:87], v[0:3], 0
	v_mfma_f32_32x32x16_f16 v[0:15], v[88:91], v[210:213], v[0:15]
	v_mfma_f32_32x32x16_f16 v[0:15], v[92:95], v[214:217], v[0:15]
	s_nop 8
	v_max_i32_e32 v16, 0, v16
	v_max_i32_e32 v17, 0, v17
	v_pk_fma_f32 v[238:239], v[16:17], v[68:69], 0 op_sel_hi:[1,1,0]
	v_max_i32_e32 v18, 0, v18
	v_max_i32_e32 v19, 0, v19
	v_mfma_f32_32x32x16_f16 v[0:15], v[96:99], v[218:221], v[0:15]
	v_pk_fma_f32 v[238:239], v[18:19], v[70:71], v[238:239]
	v_max_i32_e32 v20, 0, v20
	v_max_i32_e32 v21, 0, v21
	v_pk_fma_f32 v[238:239], v[20:21], v[72:73], v[238:239]
	v_max_i32_e32 v22, 0, v22
	v_mfma_f32_32x32x16_f16 v[0:15], v[100:103], v[222:225], v[0:15]
	v_max_i32_e32 v23, 0, v23
	v_pk_fma_f32 v[238:239], v[22:23], v[74:75], v[238:239]
	v_max_i32_e32 v24, 0, v24
	v_max_i32_e32 v25, 0, v25
	v_pk_fma_f32 v[238:239], v[24:25], v[76:77], v[238:239]
	v_mfma_f32_32x32x16_f16 v[0:15], v[104:107], v[226:229], v[0:15]
	v_max_i32_e32 v26, 0, v26
	v_max_i32_e32 v27, 0, v27
	v_pk_fma_f32 v[238:239], v[26:27], v[78:79], v[238:239]
	v_max_i32_e32 v28, 0, v28
	v_max_i32_e32 v29, 0, v29
	v_mfma_f32_32x32x16_f16 v[0:15], v[108:111], v[230:233], v[0:15]
	v_pk_fma_f32 v[238:239], v[28:29], v[80:81], v[238:239]
	v_max_i32_e32 v30, 0, v30
	v_max_i32_e32 v31, 0, v31
	v_pk_fma_f32 v[238:239], v[30:31], v[82:83], v[238:239]
	v_mfma_f32_32x32x16_f16 v[0:15], v[112:115], v[234:237], v[0:15]
	v_add_f32_e32 v240, v238, v239
	v_mov_b32_e32 v241, v240
	v_lshlrev_b32_e32 v242, 2, v32
	s_nop 0
	v_permlane32_swap_b32_e32 v241, v240
	v_add_f32_e32 v241, v241, v240
	s_mov_b64 exec, s[4:5]
	global_store_dword v242, v241, s[18:19] offset:256
	s_mov_b64 exec, -1
	s_waitcnt lgkmcnt(0)
; #define LAS __attribute__((address_space(3)))
; DI void indexer_tile(const LAS unsigned char* buf, const f16x8 (&af)[2][8], const f32x4 (&wv)[2][4], float* sc0, float* sc1, int kt, int r32, int h2) {
;     ...
;     for (int sub = 0; sub < 2; ++sub) {
;         f32x16 c0, c1;
; #pragma unroll
;         for (int i = 0; i < 16; ++i) { c0[i] = 0.f; c1[i] = 0.f; }
; #pragma unroll
;         for (int ks = 0; ks < 8; ++ks) { c0 = __builtin_amdgcn_mfma_f32_32x32x16_f16(af[0][ks], bfr[sub][ks], c0, 0, 0, 0); c1 = __builtin_amdgcn_mfma_f32_32x32x16_f16(af[1][ks], bfr[sub][ks], c1, 0, 0, 0); }
;         f32x2_t a0 = {0.f, 0.f}, a1 = {0.f, 0.f};
; #pragma unroll
;         for (int q = 0; q < 4; ++q)
; #pragma unroll
;             for (int e = 0; e < 4; e += 2) {
;                 const f32x2_t r0 = {relu1(c0[4 * q + e]), relu1(c0[4 * q + e + 1])};
;                 const f32x2_t r1 = {relu1(c1[4 * q + e]), relu1(c1[4 * q + e + 1])};
;                 const f32x2_t w0 = {wv[0][q][e], wv[0][q][e + 1]}, w1 = {wv[1][q][e], wv[1][q][e + 1]};
;                 a0 = __builtin_elementwise_fma(r0, w0, a0); a1 = __builtin_elementwise_fma(r1, w1, a1); }
;         float s0 = a0.x + a0.y, s1 = a1.x + a1.y;
;         s0 += __shfl_xor(s0, 32); s1 += __shfl_xor(s1, 32);
;         if (h2 == 0) { sc0[kt * 64 + 32 * sub + r32] = s0; sc1[kt * 64 + 32 * sub + r32] = s1; }
;     }
; DI void indexer_phase(const unsigned short* QI, const unsigned short* KI16, const float* WI, float* SC, LAS unsigned char* lds, int tid, int bid, int G) {
;     ...
;                 if (kt + 1 >= nt) break;
;                 if (kt + 3 < nt) { const unsigned short* p = src + (size_t)(kt + 3) * 64 * 128; b0 = *(const u32x4*)p; b1 = *(const u32x4*)(p + 32 * 128); }
;                 indexer_tile(buf1, af, wv, sc0, sc1, kt + 1, r32, h2);
;                 if (kt + 2 < nt) { *(LAS u32x4*)(buf0 + key0 * KT_ROWB + ch * 16) = a0; *(LAS u32x4*)(buf0 + (key0 + 32) * KT_ROWB + ch * 16) = a1; }
;                 __syncthreads();
	v_mfma_f32_32x32x16_f16 v[16:31], v[36:39], v[176:179], 0
	v_mfma_f32_32x32x16_f16 v[16:31], v[40:43], v[172:175], v[16:31]
	v_mfma_f32_32x32x16_f16 v[16:31], v[44:47], v[168:171], v[16:31]
	s_nop 8
	v_max_i32_e32 v0, 0, v0
	v_max_i32_e32 v1, 0, v1
	v_pk_fma_f32 v[244:245], v[0:1], v[116:117], 0 op_sel_hi:[1,1,0]
	v_max_i32_e32 v2, 0, v2
	v_max_i32_e32 v3, 0, v3
	v_mfma_f32_32x32x16_f16 v[16:31], v[48:51], v[164:167], v[16:31]
	v_pk_fma_f32 v[244:245], v[2:3], v[118:119], v[244:245]
	v_max_i32_e32 v4, 0, v4
	v_max_i32_e32 v5, 0, v5
	v_pk_fma_f32 v[244:245], v[4:5], v[120:121], v[244:245]
	v_max_i32_e32 v6, 0, v6
	v_mfma_f32_32x32x16_f16 v[16:31], v[52:55], v[160:163], v[16:31]
	v_max_i32_e32 v7, 0, v7
	v_pk_fma_f32 v[244:245], v[6:7], v[122:123], v[244:245]
	v_max_i32_e32 v8, 0, v8
	v_max_i32_e32 v9, 0, v9
	v_pk_fma_f32 v[244:245], v[8:9], v[124:125], v[244:245]
	v_mfma_f32_32x32x16_f16 v[16:31], v[56:59], v[156:159], v[16:31]
	v_max_i32_e32 v10, 0, v10
	v_max_i32_e32 v11, 0, v11
	v_pk_fma_f32 v[244:245], v[10:11], v[126:127], v[244:245]
	v_max_i32_e32 v12, 0, v12
	v_max_i32_e32 v13, 0, v13
	v_mfma_f32_32x32x16_f16 v[16:31], v[60:63], v[152:155], v[16:31]
	v_pk_fma_f32 v[244:245], v[12:13], v[128:129], v[244:245]
	v_max_i32_e32 v14, 0, v14
	v_max_i32_e32 v15, 0, v15
	v_pk_fma_f32 v[244:245], v[14:15], v[130:131], v[244:245]
	v_mfma_f32_32x32x16_f16 v[16:31], v[64:67], v[148:151], v[16:31]
	v_add_f32_e32 v246, v244, v245
	v_mov_b32_e32 v247, v246
	v_lshlrev_b32_e32 v248, 2, v32
	s_nop 0
	v_permlane32_swap_b32_e32 v247, v246
	v_add_f32_e32 v247, v247, v246
	s_mov_b64 exec, s[4:5]
	global_store_dword v248, v247, s[20:21] offset:256
	s_mov_b64 exec, -1
	v_mfma_f32_32x32x16_f16 v[0:15], v[84:87], v[176:179], 0
	v_mfma_f32_32x32x16_f16 v[0:15], v[88:91], v[172:175], v[0:15]
	v_mfma_f32_32x32x16_f16 v[0:15], v[92:95], v[168:171], v[0:15]
	s_nop 8
	v_max_i32_e32 v16, 0, v16
	v_max_i32_e32 v17, 0, v17
	v_pk_fma_f32 v[238:239], v[16:17], v[68:69], 0 op_sel_hi:[1,1,0]
	v_max_i32_e32 v18, 0, v18
	v_max_i32_e32 v19, 0, v19
	v_mfma_f32_32x32x16_f16 v[0:15], v[96:99], v[164:167], v[0:15]
	v_pk_fma_f32 v[238:239], v[18:19], v[70:71], v[238:239]
	v_max_i32_e32 v20, 0, v20
	v_max_i32_e32 v21, 0, v21
	v_pk_fma_f32 v[238:239], v[20:21], v[72:73], v[238:239]
	v_max_i32_e32 v22, 0, v22
	v_mfma_f32_32x32x16_f16 v[0:15], v[100:103], v[160:163], v[0:15]
	v_max_i32_e32 v23, 0, v23
	v_pk_fma_f32 v[238:239], v[22:23], v[74:75], v[238:239]
	v_max_i32_e32 v24, 0, v24
	v_max_i32_e32 v25, 0, v25
	v_pk_fma_f32 v[238:239], v[24:25], v[76:77], v[238:239]
	v_mfma_f32_32x32x16_f16 v[0:15], v[104:107], v[156:159], v[0:15]
	v_max_i32_e32 v26, 0, v26
	v_max_i32_e32 v27, 0, v27
	v_pk_fma_f32 v[238:239], v[26:27], v[78:79], v[238:239]
	v_max_i32_e32 v28, 0, v28
	v_max_i32_e32 v29, 0, v29
	v_mfma_f32_32x32x16_f16 v[0:15], v[108:111], v[152:155], v[0:15]
	v_pk_fma_f32 v[238:239], v[28:29], v[80:81], v[238:239]
	v_max_i32_e32 v30, 0, v30
	v_max_i32_e32 v31, 0, v31
	v_pk_fma_f32 v[238:239], v[30:31], v[82:83], v[238:239]
	v_mfma_f32_32x32x16_f16 v[0:15], v[112:115], v[148:151], v[0:15]
	v_add_f32_e32 v240, v238, v239
	v_mov_b32_e32 v241, v240
	v_lshlrev_b32_e32 v242, 2, v32
	s_nop 0
	v_permlane32_swap_b32_e32 v241, v240
	v_add_f32_e32 v241, v241, v240
	s_mov_b64 exec, s[4:5]
	global_store_dword v242, v241, s[18:19] offset:384
	s_mov_b64 exec, -1
	s_nop 11
	v_max_i32_e32 v0, 0, v0
	v_max_i32_e32 v1, 0, v1
	v_pk_fma_f32 v[244:245], v[0:1], v[116:117], 0 op_sel_hi:[1,1,0]
	v_max_i32_e32 v2, 0, v2
	v_max_i32_e32 v3, 0, v3
	v_pk_fma_f32 v[244:245], v[2:3], v[118:119], v[244:245]
	v_max_i32_e32 v4, 0, v4
	v_max_i32_e32 v5, 0, v5
	v_pk_fma_f32 v[244:245], v[4:5], v[120:121], v[244:245]
	v_max_i32_e32 v6, 0, v6
	v_max_i32_e32 v7, 0, v7
	v_pk_fma_f32 v[244:245], v[6:7], v[122:123], v[244:245]
	v_max_i32_e32 v8, 0, v8
	v_max_i32_e32 v9, 0, v9
	v_pk_fma_f32 v[244:245], v[8:9], v[124:125], v[244:245]
	v_max_i32_e32 v10, 0, v10
	v_max_i32_e32 v11, 0, v11
	v_pk_fma_f32 v[244:245], v[10:11], v[126:127], v[244:245]
	v_max_i32_e32 v12, 0, v12
	v_max_i32_e32 v13, 0, v13
	v_pk_fma_f32 v[244:245], v[12:13], v[128:129], v[244:245]
	v_max_i32_e32 v14, 0, v14
	v_max_i32_e32 v15, 0, v15
	v_pk_fma_f32 v[244:245], v[14:15], v[130:131], v[244:245]
	v_add_f32_e32 v246, v244, v245
	v_mov_b32_e32 v247, v246
	v_lshlrev_b32_e32 v248, 2, v32
	s_nop 0
	v_permlane32_swap_b32_e32 v247, v246
	v_add_f32_e32 v247, v247, v246
	s_mov_b64 exec, s[4:5]
	global_store_dword v248, v247, s[20:21] offset:384
	s_mov_b64 exec, -1
	s_andn2_b64 vcc, exec, s[22:23]
	s_cbranch_vccnz .LBB0_1824
	s_waitcnt vmcnt(8)
	ds_write_b128 v209, v[132:135]
	ds_write_b128 v209, v[136:139] offset:8704
	s_branch .LBB0_1824

; #define LAS __attribute__((address_space(3)))
; DI void indexer_tile(const LAS unsigned char* buf, const f16x8 (&af)[2][8], const f32x4 (&wv)[2][4], float* sc0, float* sc1, int kt, int r32, int h2) {
;     ...
;     f16x8 bfr[2][8];
; #pragma unroll
;     for (int sub = 0; sub < 2; ++sub)
; #pragma unroll
;         for (int ks = 0; ks < 8; ++ks) bfr[sub][ks] = *(const LAS f16x8*)(buf + (32 * sub + r32) * KT_ROWB + (16 * ks + 8 * h2) * 2);
;     __builtin_amdgcn_sched_barrier(0);
; #pragma unroll
;     for (int sub = 0; sub < 2; ++sub) {
;         f32x16 c0, c1;
; #pragma unroll
;         for (int i = 0; i < 16; ++i) { c0[i] = 0.f; c1[i] = 0.f; }
; #pragma unroll
;         for (int ks = 0; ks < 8; ++ks) { c0 = __builtin_amdgcn_mfma_f32_32x32x16_f16(af[0][ks], bfr[sub][ks], c0, 0, 0, 0); c1 = __builtin_amdgcn_mfma_f32_32x32x16_f16(af[1][ks], bfr[sub][ks], c1, 0, 0, 0); }
;         f32x2_t a0 = {0.f, 0.f}, a1 = {0.f, 0.f};
; #pragma unroll
;         for (int q = 0; q < 4; ++q)
; #pragma unroll
;             for (int e = 0; e < 4; e += 2) {
;                 const f32x2_t r0 = {relu1(c0[4 * q + e]), relu1(c0[4 * q + e + 1])};
;                 const f32x2_t r1 = {relu1(c1[4 * q + e]), relu1(c1[4 * q + e + 1])};
;                 const f32x2_t w0 = {wv[0][q][e], wv[0][q][e + 1]}, w1 = {wv[1][q][e], wv[1][q][e + 1]};
;                 a0 = __builtin_elementwise_fma(r0, w0, a0); a1 = __builtin_elementwise_fma(r1, w1, a1); }
;         float s0 = a0.x + a0.y, s1 = a1.x + a1.y;
;         s0 += __shfl_xor(s0, 32); s1 += __shfl_xor(s1, 32);
;         if (h2 == 0) { sc0[kt * 64 + 32 * sub + r32] = s0; sc1[kt * 64 + 32 * sub + r32] = s1; }
;     }
.LBB0_1847:
	ds_read_b128 v[0:3], v207
	ds_read_b128 v[210:213], v207 offset:32
	ds_read_b128 v[214:217], v207 offset:64
	ds_read_b128 v[218:221], v207 offset:96
	ds_read_b128 v[222:225], v207 offset:128
	ds_read_b128 v[226:229], v207 offset:160
	ds_read_b128 v[230:233], v207 offset:192
	ds_read_b128 v[234:237], v207 offset:224
	ds_read_b128 v[174:177], v207 offset:8704
	ds_read_b128 v[170:173], v207 offset:8736
	ds_read_b128 v[166:169], v207 offset:8768
	ds_read_b128 v[162:165], v207 offset:8800
	ds_read_b128 v[158:161], v207 offset:8832
	ds_read_b128 v[154:157], v207 offset:8864
	ds_read_b128 v[150:153], v207 offset:8896
	ds_read_b128 v[146:149], v207 offset:8928
	s_waitcnt lgkmcnt(15)
	v_mfma_f32_32x32x16_f16 v[16:31], v[34:37], v[0:3], 0
	s_waitcnt lgkmcnt(14)
	v_mfma_f32_32x32x16_f16 v[16:31], v[38:41], v[210:213], v[16:31]
	s_waitcnt lgkmcnt(13)
	v_mfma_f32_32x32x16_f16 v[16:31], v[42:45], v[214:217], v[16:31]
	s_waitcnt lgkmcnt(12)
	v_mfma_f32_32x32x16_f16 v[16:31], v[46:49], v[218:221], v[16:31]
	s_waitcnt lgkmcnt(11)
	v_mfma_f32_32x32x16_f16 v[16:31], v[50:53], v[222:225], v[16:31]
	s_waitcnt lgkmcnt(10)
	v_mfma_f32_32x32x16_f16 v[16:31], v[54:57], v[226:229], v[16:31]
	s_waitcnt lgkmcnt(9)
	v_mfma_f32_32x32x16_f16 v[16:31], v[58:61], v[230:233], v[16:31]
	s_waitcnt lgkmcnt(8)
	v_mfma_f32_32x32x16_f16 v[16:31], v[62:65], v[234:237], v[16:31]
	v_mfma_f32_32x32x16_f16 v[0:15], v[82:85], v[0:3], 0
	v_mfma_f32_32x32x16_f16 v[0:15], v[86:89], v[210:213], v[0:15]
	v_mfma_f32_32x32x16_f16 v[0:15], v[90:93], v[214:217], v[0:15]
	s_nop 8
	v_max_i32_e32 v16, 0, v16
	v_max_i32_e32 v17, 0, v17
	v_pk_fma_f32 v[238:239], v[16:17], v[66:67], 0 op_sel_hi:[1,1,0]
	v_max_i32_e32 v18, 0, v18
	v_max_i32_e32 v19, 0, v19
	v_mfma_f32_32x32x16_f16 v[0:15], v[94:97], v[218:221], v[0:15]
	v_pk_fma_f32 v[238:239], v[18:19], v[68:69], v[238:239]
	v_max_i32_e32 v20, 0, v20
	v_max_i32_e32 v21, 0, v21
	v_pk_fma_f32 v[238:239], v[20:21], v[70:71], v[238:239]
	v_max_i32_e32 v22, 0, v22
	v_mfma_f32_32x32x16_f16 v[0:15], v[98:101], v[222:225], v[0:15]
	v_max_i32_e32 v23, 0, v23
	v_pk_fma_f32 v[238:239], v[22:23], v[72:73], v[238:239]
	v_max_i32_e32 v24, 0, v24
	v_max_i32_e32 v25, 0, v25
	v_pk_fma_f32 v[238:239], v[24:25], v[74:75], v[238:239]
	v_mfma_f32_32x32x16_f16 v[0:15], v[102:105], v[226:229], v[0:15]
	v_max_i32_e32 v26, 0, v26
	v_max_i32_e32 v27, 0, v27
	v_pk_fma_f32 v[238:239], v[26:27], v[76:77], v[238:239]
	v_max_i32_e32 v28, 0, v28
	v_max_i32_e32 v29, 0, v29
	v_mfma_f32_32x32x16_f16 v[0:15], v[106:109], v[230:233], v[0:15]
	v_pk_fma_f32 v[238:239], v[28:29], v[78:79], v[238:239]
	v_max_i32_e32 v30, 0, v30
	v_max_i32_e32 v31, 0, v31
	v_pk_fma_f32 v[238:239], v[30:31], v[80:81], v[238:239]
	v_mfma_f32_32x32x16_f16 v[0:15], v[110:113], v[234:237], v[0:15]
	v_add_f32_e32 v240, v238, v239
	v_mov_b32_e32 v241, v240
	v_lshlrev_b32_e32 v242, 2, v32
	s_nop 0
	v_permlane32_swap_b32_e32 v241, v240
	v_add_f32_e32 v241, v241, v240
	s_mov_b64 exec, s[4:5]
	global_store_dword v242, v241, s[24:25]
	s_mov_b64 exec, -1
	s_waitcnt lgkmcnt(0)
; DI void indexer_tile(const LAS unsigned char* buf, const f16x8 (&af)[2][8], const f32x4 (&wv)[2][4], float* sc0, float* sc1, int kt, int r32, int h2) {
;     ...
;     for (int sub = 0; sub < 2; ++sub) {
;         f32x16 c0, c1;
; #pragma unroll
;         for (int i = 0; i < 16; ++i) { c0[i] = 0.f; c1[i] = 0.f; }
; #pragma unroll
;         for (int ks = 0; ks < 8; ++ks) { c0 = __builtin_amdgcn_mfma_f32_32x32x16_f16(af[0][ks], bfr[sub][ks], c0, 0, 0, 0); c1 = __builtin_amdgcn_mfma_f32_32x32x16_f16(af[1][ks], bfr[sub][ks], c1, 0, 0, 0); }
;         f32x2_t a0 = {0.f, 0.f}, a1 = {0.f, 0.f};
; #pragma unroll
;         for (int q = 0; q < 4; ++q)
; #pragma unroll
;             for (int e = 0; e < 4; e += 2) {
;                 const f32x2_t r0 = {relu1(c0[4 * q + e]), relu1(c0[4 * q + e + 1])};
;                 const f32x2_t r1 = {relu1(c1[4 * q + e]), relu1(c1[4 * q + e + 1])};
;                 const f32x2_t w0 = {wv[0][q][e], wv[0][q][e + 1]}, w1 = {wv[1][q][e], wv[1][q][e + 1]};
;                 a0 = __builtin_elementwise_fma(r0, w0, a0); a1 = __builtin_elementwise_fma(r1, w1, a1); }
;         float s0 = a0.x + a0.y, s1 = a1.x + a1.y;
;         s0 += __shfl_xor(s0, 32); s1 += __shfl_xor(s1, 32);
;         if (h2 == 0) { sc0[kt * 64 + 32 * sub + r32] = s0; sc1[kt * 64 + 32 * sub + r32] = s1; }
;     }
	v_mfma_f32_32x32x16_f16 v[16:31], v[34:37], v[174:177], 0
	v_mfma_f32_32x32x16_f16 v[16:31], v[38:41], v[170:173], v[16:31]
	v_mfma_f32_32x32x16_f16 v[16:31], v[42:45], v[166:169], v[16:31]
	s_nop 8
	v_max_i32_e32 v0, 0, v0
	v_max_i32_e32 v1, 0, v1
	v_pk_fma_f32 v[244:245], v[0:1], v[114:115], 0 op_sel_hi:[1,1,0]
	v_max_i32_e32 v2, 0, v2
	v_max_i32_e32 v3, 0, v3
	v_mfma_f32_32x32x16_f16 v[16:31], v[46:49], v[162:165], v[16:31]
	v_pk_fma_f32 v[244:245], v[2:3], v[116:117], v[244:245]
	v_max_i32_e32 v4, 0, v4
	v_max_i32_e32 v5, 0, v5
	v_pk_fma_f32 v[244:245], v[4:5], v[118:119], v[244:245]
	v_max_i32_e32 v6, 0, v6
	v_mfma_f32_32x32x16_f16 v[16:31], v[50:53], v[158:161], v[16:31]
	v_max_i32_e32 v7, 0, v7
	v_pk_fma_f32 v[244:245], v[6:7], v[120:121], v[244:245]
	v_max_i32_e32 v8, 0, v8
	v_max_i32_e32 v9, 0, v9
	v_pk_fma_f32 v[244:245], v[8:9], v[122:123], v[244:245]
	v_mfma_f32_32x32x16_f16 v[16:31], v[54:57], v[154:157], v[16:31]
	v_max_i32_e32 v10, 0, v10
	v_max_i32_e32 v11, 0, v11
	v_pk_fma_f32 v[244:245], v[10:11], v[124:125], v[244:245]
	v_max_i32_e32 v12, 0, v12
	v_max_i32_e32 v13, 0, v13
	v_mfma_f32_32x32x16_f16 v[16:31], v[58:61], v[150:153], v[16:31]
	v_pk_fma_f32 v[244:245], v[12:13], v[126:127], v[244:245]
	v_max_i32_e32 v14, 0, v14
	v_max_i32_e32 v15, 0, v15
	v_pk_fma_f32 v[244:245], v[14:15], v[128:129], v[244:245]
	v_mfma_f32_32x32x16_f16 v[16:31], v[62:65], v[146:149], v[16:31]
	v_add_f32_e32 v246, v244, v245
	v_mov_b32_e32 v247, v246
	v_lshlrev_b32_e32 v248, 2, v32
	s_nop 0
	v_permlane32_swap_b32_e32 v247, v246
	v_add_f32_e32 v247, v247, v246
	s_mov_b64 exec, s[4:5]
	global_store_dword v248, v247, s[26:27]
	s_mov_b64 exec, -1
	v_mfma_f32_32x32x16_f16 v[0:15], v[82:85], v[174:177], 0
	v_mfma_f32_32x32x16_f16 v[0:15], v[86:89], v[170:173], v[0:15]
	v_mfma_f32_32x32x16_f16 v[0:15], v[90:93], v[166:169], v[0:15]
	s_nop 8
	v_max_i32_e32 v16, 0, v16
	v_max_i32_e32 v17, 0, v17
	v_pk_fma_f32 v[238:239], v[16:17], v[66:67], 0 op_sel_hi:[1,1,0]
	v_max_i32_e32 v18, 0, v18
	v_max_i32_e32 v19, 0, v19
	v_mfma_f32_32x32x16_f16 v[0:15], v[94:97], v[162:165], v[0:15]
	v_pk_fma_f32 v[238:239], v[18:19], v[68:69], v[238:239]
	v_max_i32_e32 v20, 0, v20
	v_max_i32_e32 v21, 0, v21
	v_pk_fma_f32 v[238:239], v[20:21], v[70:71], v[238:239]
	v_max_i32_e32 v22, 0, v22
	v_mfma_f32_32x32x16_f16 v[0:15], v[98:101], v[158:161], v[0:15]
	v_max_i32_e32 v23, 0, v23
	v_pk_fma_f32 v[238:239], v[22:23], v[72:73], v[238:239]
	v_max_i32_e32 v24, 0, v24
	v_max_i32_e32 v25, 0, v25
	v_pk_fma_f32 v[238:239], v[24:25], v[74:75], v[238:239]
	v_mfma_f32_32x32x16_f16 v[0:15], v[102:105], v[154:157], v[0:15]
	v_max_i32_e32 v26, 0, v26
	v_max_i32_e32 v27, 0, v27
	v_pk_fma_f32 v[238:239], v[26:27], v[76:77], v[238:239]
	v_max_i32_e32 v28, 0, v28
	v_max_i32_e32 v29, 0, v29
	v_mfma_f32_32x32x16_f16 v[0:15], v[106:109], v[150:153], v[0:15]
	v_pk_fma_f32 v[238:239], v[28:29], v[78:79], v[238:239]
	v_max_i32_e32 v30, 0, v30
	v_max_i32_e32 v31, 0, v31
	v_pk_fma_f32 v[238:239], v[30:31], v[80:81], v[238:239]
	v_mfma_f32_32x32x16_f16 v[0:15], v[110:113], v[146:149], v[0:15]
	v_add_f32_e32 v240, v238, v239
	v_mov_b32_e32 v241, v240
	v_lshlrev_b32_e32 v242, 2, v32
	s_nop 0
	v_permlane32_swap_b32_e32 v241, v240
	v_add_f32_e32 v241, v241, v240
	s_mov_b64 exec, s[4:5]
	global_store_dword v242, v241, s[24:25] offset:128
	s_mov_b64 exec, -1
	s_nop 11
	v_max_i32_e32 v0, 0, v0
	v_max_i32_e32 v1, 0, v1
	v_pk_fma_f32 v[244:245], v[0:1], v[114:115], 0 op_sel_hi:[1,1,0]
	v_max_i32_e32 v2, 0, v2
	v_max_i32_e32 v3, 0, v3
	v_pk_fma_f32 v[244:245], v[2:3], v[116:117], v[244:245]
	v_max_i32_e32 v4, 0, v4
	v_max_i32_e32 v5, 0, v5
	v_pk_fma_f32 v[244:245], v[4:5], v[118:119], v[244:245]
	v_max_i32_e32 v6, 0, v6
	v_max_i32_e32 v7, 0, v7
	v_pk_fma_f32 v[244:245], v[6:7], v[120:121], v[244:245]
	v_max_i32_e32 v8, 0, v8
	v_max_i32_e32 v9, 0, v9
	v_pk_fma_f32 v[244:245], v[8:9], v[122:123], v[244:245]
	v_max_i32_e32 v10, 0, v10
	v_max_i32_e32 v11, 0, v11
	v_pk_fma_f32 v[244:245], v[10:11], v[124:125], v[244:245]
	v_max_i32_e32 v12, 0, v12
	v_max_i32_e32 v13, 0, v13
	v_pk_fma_f32 v[244:245], v[12:13], v[126:127], v[244:245]
	v_max_i32_e32 v14, 0, v14
	v_max_i32_e32 v15, 0, v15
	v_pk_fma_f32 v[244:245], v[14:15], v[128:129], v[244:245]
	v_add_f32_e32 v246, v244, v245
	v_mov_b32_e32 v247, v246
	v_lshlrev_b32_e32 v248, 2, v32
	s_nop 0
	v_permlane32_swap_b32_e32 v247, v246
	v_add_f32_e32 v247, v247, v246
	s_mov_b64 exec, s[4:5]
	global_store_dword v248, v247, s[26:27] offset:128
	s_mov_b64 exec, -1
	s_add_i32 s47, s11, -3
	s_cmp_lt_u32 s47, s42
	s_cselect_b64 s[30:31], -1, 0
	s_cmp_ge_u32 s47, s42
	s_cbranch_scc1 .LBB0_1853
	s_waitcnt vmcnt(8)
	ds_write_b128 v209, v[134:137] offset:17408
	ds_write_b128 v209, v[142:145] offset:26112

; #define LAS __attribute__((address_space(3)))
; DI void indexer_tile(const LAS unsigned char* buf, const f16x8 (&af)[2][8], const f32x4 (&wv)[2][4], float* sc0, float* sc1, int kt, int r32, int h2) {
;     ...
;     f16x8 bfr[2][8];
; #pragma unroll
;     for (int sub = 0; sub < 2; ++sub)
; #pragma unroll
;         for (int ks = 0; ks < 8; ++ks) bfr[sub][ks] = *(const LAS f16x8*)(buf + (32 * sub + r32) * KT_ROWB + (16 * ks + 8 * h2) * 2);
;     __builtin_amdgcn_sched_barrier(0);
; #pragma unroll
;     for (int sub = 0; sub < 2; ++sub) {
;         f32x16 c0, c1;
; #pragma unroll
;         for (int i = 0; i < 16; ++i) { c0[i] = 0.f; c1[i] = 0.f; }
; #pragma unroll
;         for (int ks = 0; ks < 8; ++ks) { c0 = __builtin_amdgcn_mfma_f32_32x32x16_f16(af[0][ks], bfr[sub][ks], c0, 0, 0, 0); c1 = __builtin_amdgcn_mfma_f32_32x32x16_f16(af[1][ks], bfr[sub][ks], c1, 0, 0, 0); }
;         f32x2_t a0 = {0.f, 0.f}, a1 = {0.f, 0.f};
; #pragma unroll
;         for (int q = 0; q < 4; ++q)
; #pragma unroll
;             for (int e = 0; e < 4; e += 2) {
;                 const f32x2_t r0 = {relu1(c0[4 * q + e]), relu1(c0[4 * q + e + 1])};
;                 const f32x2_t r1 = {relu1(c1[4 * q + e]), relu1(c1[4 * q + e + 1])};
;                 const f32x2_t w0 = {wv[0][q][e], wv[0][q][e + 1]}, w1 = {wv[1][q][e], wv[1][q][e + 1]};
;                 a0 = __builtin_elementwise_fma(r0, w0, a0); a1 = __builtin_elementwise_fma(r1, w1, a1); }
;         float s0 = a0.x + a0.y, s1 = a1.x + a1.y;
;         s0 += __shfl_xor(s0, 32); s1 += __shfl_xor(s1, 32);
;         if (h2 == 0) { sc0[kt * 64 + 32 * sub + r32] = s0; sc1[kt * 64 + 32 * sub + r32] = s1; }
;     }
.LBB0_1856:
	ds_read_b128 v[0:3], v207 offset:17408
	ds_read_b128 v[210:213], v207 offset:17440
	ds_read_b128 v[214:217], v207 offset:17472
	ds_read_b128 v[218:221], v207 offset:17504
	ds_read_b128 v[222:225], v207 offset:17536
	ds_read_b128 v[226:229], v207 offset:17568
	ds_read_b128 v[230:233], v207 offset:17600
	ds_read_b128 v[234:237], v207 offset:17632
	ds_read_b128 v[174:177], v207 offset:26112
	ds_read_b128 v[170:173], v207 offset:26144
	ds_read_b128 v[166:169], v207 offset:26176
	ds_read_b128 v[162:165], v207 offset:26208
	ds_read_b128 v[158:161], v207 offset:26240
	ds_read_b128 v[154:157], v207 offset:26272
	ds_read_b128 v[150:153], v207 offset:26304
	ds_read_b128 v[146:149], v207 offset:26336
	s_waitcnt lgkmcnt(15)
	v_mfma_f32_32x32x16_f16 v[16:31], v[34:37], v[0:3], 0
	s_waitcnt lgkmcnt(14)
	v_mfma_f32_32x32x16_f16 v[16:31], v[38:41], v[210:213], v[16:31]
	s_waitcnt lgkmcnt(13)
	v_mfma_f32_32x32x16_f16 v[16:31], v[42:45], v[214:217], v[16:31]
	s_waitcnt lgkmcnt(12)
	v_mfma_f32_32x32x16_f16 v[16:31], v[46:49], v[218:221], v[16:31]
	s_waitcnt lgkmcnt(11)
	v_mfma_f32_32x32x16_f16 v[16:31], v[50:53], v[222:225], v[16:31]
	s_waitcnt lgkmcnt(10)
	v_mfma_f32_32x32x16_f16 v[16:31], v[54:57], v[226:229], v[16:31]
	s_waitcnt lgkmcnt(9)
	v_mfma_f32_32x32x16_f16 v[16:31], v[58:61], v[230:233], v[16:31]
	s_waitcnt lgkmcnt(8)
	v_mfma_f32_32x32x16_f16 v[16:31], v[62:65], v[234:237], v[16:31]
	v_mfma_f32_32x32x16_f16 v[0:15], v[82:85], v[0:3], 0
	v_mfma_f32_32x32x16_f16 v[0:15], v[86:89], v[210:213], v[0:15]
	v_mfma_f32_32x32x16_f16 v[0:15], v[90:93], v[214:217], v[0:15]
	s_nop 8
	v_max_i32_e32 v16, 0, v16
	v_max_i32_e32 v17, 0, v17
	v_pk_fma_f32 v[238:239], v[16:17], v[66:67], 0 op_sel_hi:[1,1,0]
	v_max_i32_e32 v18, 0, v18
	v_max_i32_e32 v19, 0, v19
	v_mfma_f32_32x32x16_f16 v[0:15], v[94:97], v[218:221], v[0:15]
	v_pk_fma_f32 v[238:239], v[18:19], v[68:69], v[238:239]
	v_max_i32_e32 v20, 0, v20
	v_max_i32_e32 v21, 0, v21
	v_pk_fma_f32 v[238:239], v[20:21], v[70:71], v[238:239]
	v_max_i32_e32 v22, 0, v22
	v_mfma_f32_32x32x16_f16 v[0:15], v[98:101], v[222:225], v[0:15]
	v_max_i32_e32 v23, 0, v23
	v_pk_fma_f32 v[238:239], v[22:23], v[72:73], v[238:239]
	v_max_i32_e32 v24, 0, v24
	v_max_i32_e32 v25, 0, v25
	v_pk_fma_f32 v[238:239], v[24:25], v[74:75], v[238:239]
	v_mfma_f32_32x32x16_f16 v[0:15], v[102:105], v[226:229], v[0:15]
	v_max_i32_e32 v26, 0, v26
	v_max_i32_e32 v27, 0, v27
	v_pk_fma_f32 v[238:239], v[26:27], v[76:77], v[238:239]
	v_max_i32_e32 v28, 0, v28
	v_max_i32_e32 v29, 0, v29
	v_mfma_f32_32x32x16_f16 v[0:15], v[106:109], v[230:233], v[0:15]
	v_pk_fma_f32 v[238:239], v[28:29], v[78:79], v[238:239]
	v_max_i32_e32 v30, 0, v30
	v_max_i32_e32 v31, 0, v31
	v_pk_fma_f32 v[238:239], v[30:31], v[80:81], v[238:239]
	v_mfma_f32_32x32x16_f16 v[0:15], v[110:113], v[234:237], v[0:15]
	v_add_f32_e32 v240, v238, v239
	v_mov_b32_e32 v241, v240
	v_lshlrev_b32_e32 v242, 2, v32
	s_nop 0
	v_permlane32_swap_b32_e32 v241, v240
	v_add_f32_e32 v241, v241, v240
	s_mov_b64 exec, s[4:5]
	global_store_dword v242, v241, s[24:25] offset:256
	s_mov_b64 exec, -1
	s_waitcnt lgkmcnt(0)
; #define LAS __attribute__((address_space(3)))
; DI void indexer_tile(const LAS unsigned char* buf, const f16x8 (&af)[2][8], const f32x4 (&wv)[2][4], float* sc0, float* sc1, int kt, int r32, int h2) {
;     ...
;     for (int sub = 0; sub < 2; ++sub) {
;         f32x16 c0, c1;
; #pragma unroll
;         for (int i = 0; i < 16; ++i) { c0[i] = 0.f; c1[i] = 0.f; }
; #pragma unroll
;         for (int ks = 0; ks < 8; ++ks) { c0 = __builtin_amdgcn_mfma_f32_32x32x16_f16(af[0][ks], bfr[sub][ks], c0, 0, 0, 0); c1 = __builtin_amdgcn_mfma_f32_32x32x16_f16(af[1][ks], bfr[sub][ks], c1, 0, 0, 0); }
;         f32x2_t a0 = {0.f, 0.f}, a1 = {0.f, 0.f};
; #pragma unroll
;         for (int q = 0; q < 4; ++q)
; #pragma unroll
;             for (int e = 0; e < 4; e += 2) {
;                 const f32x2_t r0 = {relu1(c0[4 * q + e]), relu1(c0[4 * q + e + 1])};
;                 const f32x2_t r1 = {relu1(c1[4 * q + e]), relu1(c1[4 * q + e + 1])};
;                 const f32x2_t w0 = {wv[0][q][e], wv[0][q][e + 1]}, w1 = {wv[1][q][e], wv[1][q][e + 1]};
;                 a0 = __builtin_elementwise_fma(r0, w0, a0); a1 = __builtin_elementwise_fma(r1, w1, a1); }
;         float s0 = a0.x + a0.y, s1 = a1.x + a1.y;
;         s0 += __shfl_xor(s0, 32); s1 += __shfl_xor(s1, 32);
;         if (h2 == 0) { sc0[kt * 64 + 32 * sub + r32] = s0; sc1[kt * 64 + 32 * sub + r32] = s1; }
;     }
; DI void indexer_phase(const unsigned short* QI, const unsigned short* KI16, const float* WI, float* SC, LAS unsigned char* lds, int tid, int bid, int G) {
;     ...
;                 if (kt + 1 >= nt) break;
;                 if (kt + 3 < nt) { const unsigned short* p = src + (size_t)(kt + 3) * 64 * 128; b0 = *(const u32x4*)p; b1 = *(const u32x4*)(p + 32 * 128); }
;                 indexer_tile(buf1, af, wv, sc0, sc1, kt + 1, r32, h2);
;                 if (kt + 2 < nt) { *(LAS u32x4*)(buf0 + key0 * KT_ROWB + ch * 16) = a0; *(LAS u32x4*)(buf0 + (key0 + 32) * KT_ROWB + ch * 16) = a1; }
;                 __syncthreads();
	v_mfma_f32_32x32x16_f16 v[16:31], v[34:37], v[174:177], 0
	v_mfma_f32_32x32x16_f16 v[16:31], v[38:41], v[170:173], v[16:31]
	v_mfma_f32_32x32x16_f16 v[16:31], v[42:45], v[166:169], v[16:31]
	s_nop 8
	v_max_i32_e32 v0, 0, v0
	v_max_i32_e32 v1, 0, v1
	v_pk_fma_f32 v[244:245], v[0:1], v[114:115], 0 op_sel_hi:[1,1,0]
	v_max_i32_e32 v2, 0, v2
	v_max_i32_e32 v3, 0, v3
	v_mfma_f32_32x32x16_f16 v[16:31], v[46:49], v[162:165], v[16:31]
	v_pk_fma_f32 v[244:245], v[2:3], v[116:117], v[244:245]
	v_max_i32_e32 v4, 0, v4
	v_max_i32_e32 v5, 0, v5
	v_pk_fma_f32 v[244:245], v[4:5], v[118:119], v[244:245]
	v_max_i32_e32 v6, 0, v6
	v_mfma_f32_32x32x16_f16 v[16:31], v[50:53], v[158:161], v[16:31]
	v_max_i32_e32 v7, 0, v7
	v_pk_fma_f32 v[244:245], v[6:7], v[120:121], v[244:245]
	v_max_i32_e32 v8, 0, v8
	v_max_i32_e32 v9, 0, v9
	v_pk_fma_f32 v[244:245], v[8:9], v[122:123], v[244:245]
	v_mfma_f32_32x32x16_f16 v[16:31], v[54:57], v[154:157], v[16:31]
	v_max_i32_e32 v10, 0, v10
	v_max_i32_e32 v11, 0, v11
	v_pk_fma_f32 v[244:245], v[10:11], v[124:125], v[244:245]
	v_max_i32_e32 v12, 0, v12
	v_max_i32_e32 v13, 0, v13
	v_mfma_f32_32x32x16_f16 v[16:31], v[58:61], v[150:153], v[16:31]
	v_pk_fma_f32 v[244:245], v[12:13], v[126:127], v[244:245]
	v_max_i32_e32 v14, 0, v14
	v_max_i32_e32 v15, 0, v15
	v_pk_fma_f32 v[244:245], v[14:15], v[128:129], v[244:245]
	v_mfma_f32_32x32x16_f16 v[16:31], v[62:65], v[146:149], v[16:31]
	v_add_f32_e32 v246, v244, v245
	v_mov_b32_e32 v247, v246
	v_lshlrev_b32_e32 v248, 2, v32
	s_nop 0
	v_permlane32_swap_b32_e32 v247, v246
	v_add_f32_e32 v247, v247, v246
	s_mov_b64 exec, s[4:5]
	global_store_dword v248, v247, s[26:27] offset:256
	s_mov_b64 exec, -1
	v_mfma_f32_32x32x16_f16 v[0:15], v[82:85], v[174:177], 0
	v_mfma_f32_32x32x16_f16 v[0:15], v[86:89], v[170:173], v[0:15]
	v_mfma_f32_32x32x16_f16 v[0:15], v[90:93], v[166:169], v[0:15]
	s_nop 8
	v_max_i32_e32 v16, 0, v16
	v_max_i32_e32 v17, 0, v17
	v_pk_fma_f32 v[238:239], v[16:17], v[66:67], 0 op_sel_hi:[1,1,0]
	v_max_i32_e32 v18, 0, v18
	v_max_i32_e32 v19, 0, v19
	v_mfma_f32_32x32x16_f16 v[0:15], v[94:97], v[162:165], v[0:15]
	v_pk_fma_f32 v[238:239], v[18:19], v[68:69], v[238:239]
	v_max_i32_e32 v20, 0, v20
	v_max_i32_e32 v21, 0, v21
	v_pk_fma_f32 v[238:239], v[20:21], v[70:71], v[238:239]
	v_max_i32_e32 v22, 0, v22
	v_mfma_f32_32x32x16_f16 v[0:15], v[98:101], v[158:161], v[0:15]
	v_max_i32_e32 v23, 0, v23
	v_pk_fma_f32 v[238:239], v[22:23], v[72:73], v[238:239]
	v_max_i32_e32 v24, 0, v24
	v_max_i32_e32 v25, 0, v25
	v_pk_fma_f32 v[238:239], v[24:25], v[74:75], v[238:239]
	v_mfma_f32_32x32x16_f16 v[0:15], v[102:105], v[154:157], v[0:15]
	v_max_i32_e32 v26, 0, v26
	v_max_i32_e32 v27, 0, v27
	v_pk_fma_f32 v[238:239], v[26:27], v[76:77], v[238:239]
	v_max_i32_e32 v28, 0, v28
	v_max_i32_e32 v29, 0, v29
	v_mfma_f32_32x32x16_f16 v[0:15], v[106:109], v[150:153], v[0:15]
	v_pk_fma_f32 v[238:239], v[28:29], v[78:79], v[238:239]
	v_max_i32_e32 v30, 0, v30
	v_max_i32_e32 v31, 0, v31
	v_pk_fma_f32 v[238:239], v[30:31], v[80:81], v[238:239]
	v_mfma_f32_32x32x16_f16 v[0:15], v[110:113], v[146:149], v[0:15]
	v_add_f32_e32 v240, v238, v239
	v_mov_b32_e32 v241, v240
	v_lshlrev_b32_e32 v242, 2, v32
	s_nop 0
	v_permlane32_swap_b32_e32 v241, v240
	v_add_f32_e32 v241, v241, v240
	s_mov_b64 exec, s[4:5]
	global_store_dword v242, v241, s[24:25] offset:384
	s_mov_b64 exec, -1
	s_nop 11
	v_max_i32_e32 v0, 0, v0
	v_max_i32_e32 v1, 0, v1
	v_pk_fma_f32 v[244:245], v[0:1], v[114:115], 0 op_sel_hi:[1,1,0]
	v_max_i32_e32 v2, 0, v2
	v_max_i32_e32 v3, 0, v3
	v_pk_fma_f32 v[244:245], v[2:3], v[116:117], v[244:245]
	v_max_i32_e32 v4, 0, v4
	v_max_i32_e32 v5, 0, v5
	v_pk_fma_f32 v[244:245], v[4:5], v[118:119], v[244:245]
	v_max_i32_e32 v6, 0, v6
	v_max_i32_e32 v7, 0, v7
	v_pk_fma_f32 v[244:245], v[6:7], v[120:121], v[244:245]
	v_max_i32_e32 v8, 0, v8
	v_max_i32_e32 v9, 0, v9
	v_pk_fma_f32 v[244:245], v[8:9], v[122:123], v[244:245]
	v_max_i32_e32 v10, 0, v10
	v_max_i32_e32 v11, 0, v11
	v_pk_fma_f32 v[244:245], v[10:11], v[124:125], v[244:245]
	v_max_i32_e32 v12, 0, v12
	v_max_i32_e32 v13, 0, v13
	v_pk_fma_f32 v[244:245], v[12:13], v[126:127], v[244:245]
	v_max_i32_e32 v14, 0, v14
	v_max_i32_e32 v15, 0, v15
	v_pk_fma_f32 v[244:245], v[14:15], v[128:129], v[244:245]
	v_add_f32_e32 v246, v244, v245
	v_mov_b32_e32 v247, v246
	v_lshlrev_b32_e32 v248, 2, v32
	s_nop 0
	v_permlane32_swap_b32_e32 v247, v246
	v_add_f32_e32 v247, v247, v246
	s_mov_b64 exec, s[4:5]
	global_store_dword v248, v247, s[26:27] offset:384
	s_mov_b64 exec, -1
	s_andn2_b64 vcc, exec, s[28:29]
	s_cbranch_vccnz .LBB0_1844
	s_waitcnt vmcnt(8)
	ds_write_b128 v209, v[130:133]
	ds_write_b128 v209, v[138:141] offset:8704
	s_branch .LBB0_1844

; #define LAS __attribute__((address_space(3)))
; DI void indexer_tile(const LAS unsigned char* buf, const f16x8 (&af)[2][8], const f32x4 (&wv)[2][4], float* sc0, float* sc1, int kt, int r32, int h2) {
;     ...
;     f16x8 bfr[2][8];
; #pragma unroll
;     for (int sub = 0; sub < 2; ++sub)
; #pragma unroll
;         for (int ks = 0; ks < 8; ++ks) bfr[sub][ks] = *(const LAS f16x8*)(buf + (32 * sub + r32) * KT_ROWB + (16 * ks + 8 * h2) * 2);
;     __builtin_amdgcn_sched_barrier(0);
; #pragma unroll
;     for (int sub = 0; sub < 2; ++sub) {
;         f32x16 c0, c1;
; #pragma unroll
;         for (int i = 0; i < 16; ++i) { c0[i] = 0.f; c1[i] = 0.f; }
; #pragma unroll
;         for (int ks = 0; ks < 8; ++ks) { c0 = __builtin_amdgcn_mfma_f32_32x32x16_f16(af[0][ks], bfr[sub][ks], c0, 0, 0, 0); c1 = __builtin_amdgcn_mfma_f32_32x32x16_f16(af[1][ks], bfr[sub][ks], c1, 0, 0, 0); }
;         f32x2_t a0 = {0.f, 0.f}, a1 = {0.f, 0.f};
; #pragma unroll
;         for (int q = 0; q < 4; ++q)
; #pragma unroll
;             for (int e = 0; e < 4; e += 2) {
;                 const f32x2_t r0 = {relu1(c0[4 * q + e]), relu1(c0[4 * q + e + 1])};
;                 const f32x2_t r1 = {relu1(c1[4 * q + e]), relu1(c1[4 * q + e + 1])};
;                 const f32x2_t w0 = {wv[0][q][e], wv[0][q][e + 1]}, w1 = {wv[1][q][e], wv[1][q][e + 1]};
;                 a0 = __builtin_elementwise_fma(r0, w0, a0); a1 = __builtin_elementwise_fma(r1, w1, a1); }
;         float s0 = a0.x + a0.y, s1 = a1.x + a1.y;
;         s0 += __shfl_xor(s0, 32); s1 += __shfl_xor(s1, 32);
;         if (h2 == 0) { sc0[kt * 64 + 32 * sub + r32] = s0; sc1[kt * 64 + 32 * sub + r32] = s1; }
;     }
.LBB0_1871:
	ds_read_b128 v[0:3], v207
	ds_read_b128 v[210:213], v207 offset:32
	ds_read_b128 v[214:217], v207 offset:64
	ds_read_b128 v[218:221], v207 offset:96
	ds_read_b128 v[222:225], v207 offset:128
	ds_read_b128 v[226:229], v207 offset:160
	ds_read_b128 v[230:233], v207 offset:192
	ds_read_b128 v[234:237], v207 offset:224
	ds_read_b128 v[176:179], v207 offset:8704
	ds_read_b128 v[172:175], v207 offset:8736
	ds_read_b128 v[168:171], v207 offset:8768
	ds_read_b128 v[164:167], v207 offset:8800
	ds_read_b128 v[160:163], v207 offset:8832
	ds_read_b128 v[156:159], v207 offset:8864
	ds_read_b128 v[152:155], v207 offset:8896
	ds_read_b128 v[148:151], v207 offset:8928
	s_waitcnt lgkmcnt(15)
	v_mfma_f32_32x32x16_f16 v[16:31], v[36:39], v[0:3], 0
	s_waitcnt lgkmcnt(14)
	v_mfma_f32_32x32x16_f16 v[16:31], v[40:43], v[210:213], v[16:31]
	s_waitcnt lgkmcnt(13)
	v_mfma_f32_32x32x16_f16 v[16:31], v[44:47], v[214:217], v[16:31]
	s_waitcnt lgkmcnt(12)
	v_mfma_f32_32x32x16_f16 v[16:31], v[48:51], v[218:221], v[16:31]
	s_waitcnt lgkmcnt(11)
	v_mfma_f32_32x32x16_f16 v[16:31], v[52:55], v[222:225], v[16:31]
	s_waitcnt lgkmcnt(10)
	v_mfma_f32_32x32x16_f16 v[16:31], v[56:59], v[226:229], v[16:31]
	s_waitcnt lgkmcnt(9)
	v_mfma_f32_32x32x16_f16 v[16:31], v[60:63], v[230:233], v[16:31]
	s_waitcnt lgkmcnt(8)
	v_mfma_f32_32x32x16_f16 v[16:31], v[64:67], v[234:237], v[16:31]
	v_mfma_f32_32x32x16_f16 v[0:15], v[84:87], v[0:3], 0
	v_mfma_f32_32x32x16_f16 v[0:15], v[88:91], v[210:213], v[0:15]
	v_mfma_f32_32x32x16_f16 v[0:15], v[92:95], v[214:217], v[0:15]
	s_nop 8
	v_max_i32_e32 v16, 0, v16
	v_max_i32_e32 v17, 0, v17
	v_pk_fma_f32 v[238:239], v[16:17], v[68:69], 0 op_sel_hi:[1,1,0]
	v_max_i32_e32 v18, 0, v18
	v_max_i32_e32 v19, 0, v19
	v_mfma_f32_32x32x16_f16 v[0:15], v[96:99], v[218:221], v[0:15]
	v_pk_fma_f32 v[238:239], v[18:19], v[70:71], v[238:239]
	v_max_i32_e32 v20, 0, v20
	v_max_i32_e32 v21, 0, v21
	v_pk_fma_f32 v[238:239], v[20:21], v[72:73], v[238:239]
	v_max_i32_e32 v22, 0, v22
	v_mfma_f32_32x32x16_f16 v[0:15], v[100:103], v[222:225], v[0:15]
	v_max_i32_e32 v23, 0, v23
	v_pk_fma_f32 v[238:239], v[22:23], v[74:75], v[238:239]
	v_max_i32_e32 v24, 0, v24
	v_max_i32_e32 v25, 0, v25
	v_pk_fma_f32 v[238:239], v[24:25], v[76:77], v[238:239]
	v_mfma_f32_32x32x16_f16 v[0:15], v[104:107], v[226:229], v[0:15]
	v_max_i32_e32 v26, 0, v26
	v_max_i32_e32 v27, 0, v27
	v_pk_fma_f32 v[238:239], v[26:27], v[78:79], v[238:239]
	v_max_i32_e32 v28, 0, v28
	v_max_i32_e32 v29, 0, v29
	v_mfma_f32_32x32x16_f16 v[0:15], v[108:111], v[230:233], v[0:15]
	v_pk_fma_f32 v[238:239], v[28:29], v[80:81], v[238:239]
	v_max_i32_e32 v30, 0, v30
	v_max_i32_e32 v31, 0, v31
	v_pk_fma_f32 v[238:239], v[30:31], v[82:83], v[238:239]
	v_mfma_f32_32x32x16_f16 v[0:15], v[112:115], v[234:237], v[0:15]
	v_add_f32_e32 v240, v238, v239
	v_mov_b32_e32 v241, v240
	v_lshlrev_b32_e32 v242, 2, v32
	s_nop 0
	v_permlane32_swap_b32_e32 v241, v240
	v_add_f32_e32 v241, v241, v240
	s_mov_b64 exec, s[4:5]
	global_store_dword v242, v241, s[6:7]
	s_mov_b64 exec, -1
	s_waitcnt lgkmcnt(0)
; DI void indexer_tile(const LAS unsigned char* buf, const f16x8 (&af)[2][8], const f32x4 (&wv)[2][4], float* sc0, float* sc1, int kt, int r32, int h2) {
;     ...
;     for (int sub = 0; sub < 2; ++sub) {
;         f32x16 c0, c1;
; #pragma unroll
;         for (int i = 0; i < 16; ++i) { c0[i] = 0.f; c1[i] = 0.f; }
; #pragma unroll
;         for (int ks = 0; ks < 8; ++ks) { c0 = __builtin_amdgcn_mfma_f32_32x32x16_f16(af[0][ks], bfr[sub][ks], c0, 0, 0, 0); c1 = __builtin_amdgcn_mfma_f32_32x32x16_f16(af[1][ks], bfr[sub][ks], c1, 0, 0, 0); }
;         f32x2_t a0 = {0.f, 0.f}, a1 = {0.f, 0.f};
; #pragma unroll
;         for (int q = 0; q < 4; ++q)
; #pragma unroll
;             for (int e = 0; e < 4; e += 2) {
;                 const f32x2_t r0 = {relu1(c0[4 * q + e]), relu1(c0[4 * q + e + 1])};
;                 const f32x2_t r1 = {relu1(c1[4 * q + e]), relu1(c1[4 * q + e + 1])};
;                 const f32x2_t w0 = {wv[0][q][e], wv[0][q][e + 1]}, w1 = {wv[1][q][e], wv[1][q][e + 1]};
;                 a0 = __builtin_elementwise_fma(r0, w0, a0); a1 = __builtin_elementwise_fma(r1, w1, a1); }
;         float s0 = a0.x + a0.y, s1 = a1.x + a1.y;
;         s0 += __shfl_xor(s0, 32); s1 += __shfl_xor(s1, 32);
;         if (h2 == 0) { sc0[kt * 64 + 32 * sub + r32] = s0; sc1[kt * 64 + 32 * sub + r32] = s1; }
;     }
	v_mfma_f32_32x32x16_f16 v[16:31], v[36:39], v[176:179], 0
	v_mfma_f32_32x32x16_f16 v[16:31], v[40:43], v[172:175], v[16:31]
	v_mfma_f32_32x32x16_f16 v[16:31], v[44:47], v[168:171], v[16:31]
	s_nop 8
	v_max_i32_e32 v0, 0, v0
	v_max_i32_e32 v1, 0, v1
	v_pk_fma_f32 v[244:245], v[0:1], v[116:117], 0 op_sel_hi:[1,1,0]
	v_max_i32_e32 v2, 0, v2
	v_max_i32_e32 v3, 0, v3
	v_mfma_f32_32x32x16_f16 v[16:31], v[48:51], v[164:167], v[16:31]
	v_pk_fma_f32 v[244:245], v[2:3], v[118:119], v[244:245]
	v_max_i32_e32 v4, 0, v4
	v_max_i32_e32 v5, 0, v5
	v_pk_fma_f32 v[244:245], v[4:5], v[120:121], v[244:245]
	v_max_i32_e32 v6, 0, v6
	v_mfma_f32_32x32x16_f16 v[16:31], v[52:55], v[160:163], v[16:31]
	v_max_i32_e32 v7, 0, v7
	v_pk_fma_f32 v[244:245], v[6:7], v[122:123], v[244:245]
	v_max_i32_e32 v8, 0, v8
	v_max_i32_e32 v9, 0, v9
	v_pk_fma_f32 v[244:245], v[8:9], v[124:125], v[244:245]
	v_mfma_f32_32x32x16_f16 v[16:31], v[56:59], v[156:159], v[16:31]
	v_max_i32_e32 v10, 0, v10
	v_max_i32_e32 v11, 0, v11
	v_pk_fma_f32 v[244:245], v[10:11], v[126:127], v[244:245]
	v_max_i32_e32 v12, 0, v12
	v_max_i32_e32 v13, 0, v13
	v_mfma_f32_32x32x16_f16 v[16:31], v[60:63], v[152:155], v[16:31]
	v_pk_fma_f32 v[244:245], v[12:13], v[128:129], v[244:245]
	v_max_i32_e32 v14, 0, v14
	v_max_i32_e32 v15, 0, v15
	v_pk_fma_f32 v[244:245], v[14:15], v[130:131], v[244:245]
	v_mfma_f32_32x32x16_f16 v[16:31], v[64:67], v[148:151], v[16:31]
	v_add_f32_e32 v246, v244, v245
	v_mov_b32_e32 v247, v246
	v_lshlrev_b32_e32 v248, 2, v32
	s_nop 0
	v_permlane32_swap_b32_e32 v247, v246
	v_add_f32_e32 v247, v247, v246
	s_mov_b64 exec, s[4:5]
	global_store_dword v248, v247, s[8:9]
	s_mov_b64 exec, -1
	v_mfma_f32_32x32x16_f16 v[0:15], v[84:87], v[176:179], 0
	v_mfma_f32_32x32x16_f16 v[0:15], v[88:91], v[172:175], v[0:15]
	v_mfma_f32_32x32x16_f16 v[0:15], v[92:95], v[168:171], v[0:15]
	s_nop 8
	v_max_i32_e32 v16, 0, v16
	v_max_i32_e32 v17, 0, v17
	v_pk_fma_f32 v[238:239], v[16:17], v[68:69], 0 op_sel_hi:[1,1,0]
	v_max_i32_e32 v18, 0, v18
	v_max_i32_e32 v19, 0, v19
	v_mfma_f32_32x32x16_f16 v[0:15], v[96:99], v[164:167], v[0:15]
	v_pk_fma_f32 v[238:239], v[18:19], v[70:71], v[238:239]
	v_max_i32_e32 v20, 0, v20
	v_max_i32_e32 v21, 0, v21
	v_pk_fma_f32 v[238:239], v[20:21], v[72:73], v[238:239]
	v_max_i32_e32 v22, 0, v22
	v_mfma_f32_32x32x16_f16 v[0:15], v[100:103], v[160:163], v[0:15]
	v_max_i32_e32 v23, 0, v23
	v_pk_fma_f32 v[238:239], v[22:23], v[74:75], v[238:239]
	v_max_i32_e32 v24, 0, v24
	v_max_i32_e32 v25, 0, v25
	v_pk_fma_f32 v[238:239], v[24:25], v[76:77], v[238:239]
	v_mfma_f32_32x32x16_f16 v[0:15], v[104:107], v[156:159], v[0:15]
	v_max_i32_e32 v26, 0, v26
	v_max_i32_e32 v27, 0, v27
	v_pk_fma_f32 v[238:239], v[26:27], v[78:79], v[238:239]
	v_max_i32_e32 v28, 0, v28
	v_max_i32_e32 v29, 0, v29
	v_mfma_f32_32x32x16_f16 v[0:15], v[108:111], v[152:155], v[0:15]
	v_pk_fma_f32 v[238:239], v[28:29], v[80:81], v[238:239]
	v_max_i32_e32 v30, 0, v30
	v_max_i32_e32 v31, 0, v31
	v_pk_fma_f32 v[238:239], v[30:31], v[82:83], v[238:239]
	v_mfma_f32_32x32x16_f16 v[0:15], v[112:115], v[148:151], v[0:15]
	v_add_f32_e32 v240, v238, v239
	v_mov_b32_e32 v241, v240
	v_lshlrev_b32_e32 v242, 2, v32
	s_nop 0
	v_permlane32_swap_b32_e32 v241, v240
	v_add_f32_e32 v241, v241, v240
	s_mov_b64 exec, s[4:5]
	global_store_dword v242, v241, s[6:7] offset:128
	s_mov_b64 exec, -1
	s_nop 11
	v_max_i32_e32 v0, 0, v0
	v_max_i32_e32 v1, 0, v1
	v_pk_fma_f32 v[244:245], v[0:1], v[116:117], 0 op_sel_hi:[1,1,0]
	v_max_i32_e32 v2, 0, v2
	v_max_i32_e32 v3, 0, v3
	v_pk_fma_f32 v[244:245], v[2:3], v[118:119], v[244:245]
	v_max_i32_e32 v4, 0, v4
	v_max_i32_e32 v5, 0, v5
	v_pk_fma_f32 v[244:245], v[4:5], v[120:121], v[244:245]
	v_max_i32_e32 v6, 0, v6
	v_max_i32_e32 v7, 0, v7
	v_pk_fma_f32 v[244:245], v[6:7], v[122:123], v[244:245]
	v_max_i32_e32 v8, 0, v8
	v_max_i32_e32 v9, 0, v9
	v_pk_fma_f32 v[244:245], v[8:9], v[124:125], v[244:245]
	v_max_i32_e32 v10, 0, v10
	v_max_i32_e32 v11, 0, v11
	v_pk_fma_f32 v[244:245], v[10:11], v[126:127], v[244:245]
	v_max_i32_e32 v12, 0, v12
	v_max_i32_e32 v13, 0, v13
	v_pk_fma_f32 v[244:245], v[12:13], v[128:129], v[244:245]
	v_max_i32_e32 v14, 0, v14
	v_max_i32_e32 v15, 0, v15
	v_pk_fma_f32 v[244:245], v[14:15], v[130:131], v[244:245]
	v_add_f32_e32 v246, v244, v245
	v_mov_b32_e32 v247, v246
	v_lshlrev_b32_e32 v248, 2, v32
	s_nop 0
	v_permlane32_swap_b32_e32 v247, v246
	v_add_f32_e32 v247, v247, v246
	s_mov_b64 exec, s[4:5]
	global_store_dword v248, v247, s[8:9] offset:128
	s_mov_b64 exec, -1
	s_add_i32 s24, s14, -3
	s_cmp_lt_i32 s24, s41
	s_cselect_b64 s[12:13], -1, 0
	s_cmp_ge_i32 s24, s41
	s_cbranch_scc1 .LBB0_1877
	s_waitcnt vmcnt(8)
	ds_write_b128 v209, v[140:143] offset:17408
	ds_write_b128 v209, v[144:147] offset:26112

; #define LAS __attribute__((address_space(3)))
; DI void indexer_tile(const LAS unsigned char* buf, const f16x8 (&af)[2][8], const f32x4 (&wv)[2][4], float* sc0, float* sc1, int kt, int r32, int h2) {
;     ...
;     f16x8 bfr[2][8];
; #pragma unroll
;     for (int sub = 0; sub < 2; ++sub)
; #pragma unroll
;         for (int ks = 0; ks < 8; ++ks) bfr[sub][ks] = *(const LAS f16x8*)(buf + (32 * sub + r32) * KT_ROWB + (16 * ks + 8 * h2) * 2);
;     __builtin_amdgcn_sched_barrier(0);
; #pragma unroll
;     for (int sub = 0; sub < 2; ++sub) {
;         f32x16 c0, c1;
; #pragma unroll
;         for (int i = 0; i < 16; ++i) { c0[i] = 0.f; c1[i] = 0.f; }
; #pragma unroll
;         for (int ks = 0; ks < 8; ++ks) { c0 = __builtin_amdgcn_mfma_f32_32x32x16_f16(af[0][ks], bfr[sub][ks], c0, 0, 0, 0); c1 = __builtin_amdgcn_mfma_f32_32x32x16_f16(af[1][ks], bfr[sub][ks], c1, 0, 0, 0); }
;         f32x2_t a0 = {0.f, 0.f}, a1 = {0.f, 0.f};
; #pragma unroll
;         for (int q = 0; q < 4; ++q)
; #pragma unroll
;             for (int e = 0; e < 4; e += 2) {
;                 const f32x2_t r0 = {relu1(c0[4 * q + e]), relu1(c0[4 * q + e + 1])};
;                 const f32x2_t r1 = {relu1(c1[4 * q + e]), relu1(c1[4 * q + e + 1])};
;                 const f32x2_t w0 = {wv[0][q][e], wv[0][q][e + 1]}, w1 = {wv[1][q][e], wv[1][q][e + 1]};
;                 a0 = __builtin_elementwise_fma(r0, w0, a0); a1 = __builtin_elementwise_fma(r1, w1, a1); }
;         float s0 = a0.x + a0.y, s1 = a1.x + a1.y;
;         s0 += __shfl_xor(s0, 32); s1 += __shfl_xor(s1, 32);
;         if (h2 == 0) { sc0[kt * 64 + 32 * sub + r32] = s0; sc1[kt * 64 + 32 * sub + r32] = s1; }
;     }
.LBB0_1880:
	ds_read_b128 v[0:3], v207 offset:17408
	ds_read_b128 v[210:213], v207 offset:17440
	ds_read_b128 v[214:217], v207 offset:17472
	ds_read_b128 v[218:221], v207 offset:17504
	ds_read_b128 v[222:225], v207 offset:17536
	ds_read_b128 v[226:229], v207 offset:17568
	ds_read_b128 v[230:233], v207 offset:17600
	ds_read_b128 v[234:237], v207 offset:17632
	ds_read_b128 v[176:179], v207 offset:26112
	ds_read_b128 v[172:175], v207 offset:26144
	ds_read_b128 v[168:171], v207 offset:26176
	ds_read_b128 v[164:167], v207 offset:26208
	ds_read_b128 v[160:163], v207 offset:26240
	ds_read_b128 v[156:159], v207 offset:26272
	ds_read_b128 v[152:155], v207 offset:26304
	ds_read_b128 v[148:151], v207 offset:26336
	s_waitcnt lgkmcnt(15)
	v_mfma_f32_32x32x16_f16 v[16:31], v[36:39], v[0:3], 0
	s_waitcnt lgkmcnt(14)
	v_mfma_f32_32x32x16_f16 v[16:31], v[40:43], v[210:213], v[16:31]
	s_waitcnt lgkmcnt(13)
	v_mfma_f32_32x32x16_f16 v[16:31], v[44:47], v[214:217], v[16:31]
	s_waitcnt lgkmcnt(12)
	v_mfma_f32_32x32x16_f16 v[16:31], v[48:51], v[218:221], v[16:31]
	s_waitcnt lgkmcnt(11)
	v_mfma_f32_32x32x16_f16 v[16:31], v[52:55], v[222:225], v[16:31]
	s_waitcnt lgkmcnt(10)
	v_mfma_f32_32x32x16_f16 v[16:31], v[56:59], v[226:229], v[16:31]
	s_waitcnt lgkmcnt(9)
	v_mfma_f32_32x32x16_f16 v[16:31], v[60:63], v[230:233], v[16:31]
	s_waitcnt lgkmcnt(8)
	v_mfma_f32_32x32x16_f16 v[16:31], v[64:67], v[234:237], v[16:31]
	v_mfma_f32_32x32x16_f16 v[0:15], v[84:87], v[0:3], 0
	v_mfma_f32_32x32x16_f16 v[0:15], v[88:91], v[210:213], v[0:15]
	v_mfma_f32_32x32x16_f16 v[0:15], v[92:95], v[214:217], v[0:15]
	s_nop 8
	v_max_i32_e32 v16, 0, v16
	v_max_i32_e32 v17, 0, v17
	v_pk_fma_f32 v[238:239], v[16:17], v[68:69], 0 op_sel_hi:[1,1,0]
	v_max_i32_e32 v18, 0, v18
	v_max_i32_e32 v19, 0, v19
	v_mfma_f32_32x32x16_f16 v[0:15], v[96:99], v[218:221], v[0:15]
	v_pk_fma_f32 v[238:239], v[18:19], v[70:71], v[238:239]
	v_max_i32_e32 v20, 0, v20
	v_max_i32_e32 v21, 0, v21
	v_pk_fma_f32 v[238:239], v[20:21], v[72:73], v[238:239]
	v_max_i32_e32 v22, 0, v22
	v_mfma_f32_32x32x16_f16 v[0:15], v[100:103], v[222:225], v[0:15]
	v_max_i32_e32 v23, 0, v23
	v_pk_fma_f32 v[238:239], v[22:23], v[74:75], v[238:239]
	v_max_i32_e32 v24, 0, v24
	v_max_i32_e32 v25, 0, v25
	v_pk_fma_f32 v[238:239], v[24:25], v[76:77], v[238:239]
	v_mfma_f32_32x32x16_f16 v[0:15], v[104:107], v[226:229], v[0:15]
	v_max_i32_e32 v26, 0, v26
	v_max_i32_e32 v27, 0, v27
	v_pk_fma_f32 v[238:239], v[26:27], v[78:79], v[238:239]
	v_max_i32_e32 v28, 0, v28
	v_max_i32_e32 v29, 0, v29
	v_mfma_f32_32x32x16_f16 v[0:15], v[108:111], v[230:233], v[0:15]
	v_pk_fma_f32 v[238:239], v[28:29], v[80:81], v[238:239]
	v_max_i32_e32 v30, 0, v30
	v_max_i32_e32 v31, 0, v31
	v_pk_fma_f32 v[238:239], v[30:31], v[82:83], v[238:239]
	v_mfma_f32_32x32x16_f16 v[0:15], v[112:115], v[234:237], v[0:15]
	v_add_f32_e32 v240, v238, v239
	v_mov_b32_e32 v241, v240
	v_lshlrev_b32_e32 v242, 2, v32
	s_nop 0
	v_permlane32_swap_b32_e32 v241, v240
	v_add_f32_e32 v241, v241, v240
	s_mov_b64 exec, s[4:5]
	global_store_dword v242, v241, s[6:7] offset:256
	s_mov_b64 exec, -1
	s_waitcnt lgkmcnt(0)
; #define LAS __attribute__((address_space(3)))
; DI void indexer_tile(const LAS unsigned char* buf, const f16x8 (&af)[2][8], const f32x4 (&wv)[2][4], float* sc0, float* sc1, int kt, int r32, int h2) {
;     ...
;     for (int sub = 0; sub < 2; ++sub) {
;         f32x16 c0, c1;
; #pragma unroll
;         for (int i = 0; i < 16; ++i) { c0[i] = 0.f; c1[i] = 0.f; }
; #pragma unroll
;         for (int ks = 0; ks < 8; ++ks) { c0 = __builtin_amdgcn_mfma_f32_32x32x16_f16(af[0][ks], bfr[sub][ks], c0, 0, 0, 0); c1 = __builtin_amdgcn_mfma_f32_32x32x16_f16(af[1][ks], bfr[sub][ks], c1, 0, 0, 0); }
;         f32x2_t a0 = {0.f, 0.f}, a1 = {0.f, 0.f};
; #pragma unroll
;         for (int q = 0; q < 4; ++q)
; #pragma unroll
;             for (int e = 0; e < 4; e += 2) {
;                 const f32x2_t r0 = {relu1(c0[4 * q + e]), relu1(c0[4 * q + e + 1])};
;                 const f32x2_t r1 = {relu1(c1[4 * q + e]), relu1(c1[4 * q + e + 1])};
;                 const f32x2_t w0 = {wv[0][q][e], wv[0][q][e + 1]}, w1 = {wv[1][q][e], wv[1][q][e + 1]};
;                 a0 = __builtin_elementwise_fma(r0, w0, a0); a1 = __builtin_elementwise_fma(r1, w1, a1); }
;         float s0 = a0.x + a0.y, s1 = a1.x + a1.y;
;         s0 += __shfl_xor(s0, 32); s1 += __shfl_xor(s1, 32);
;         if (h2 == 0) { sc0[kt * 64 + 32 * sub + r32] = s0; sc1[kt * 64 + 32 * sub + r32] = s1; }
;     }
; DI void indexer_phase(const unsigned short* QI, const unsigned short* KI16, const float* WI, float* SC, LAS unsigned char* lds, int tid, int bid, int G) {
;     ...
;                 if (kt + 1 >= nt) break;
;                 if (kt + 3 < nt) { const unsigned short* p = src + (size_t)(kt + 3) * 64 * 128; b0 = *(const u32x4*)p; b1 = *(const u32x4*)(p + 32 * 128); }
;                 indexer_tile(buf1, af, wv, sc0, sc1, kt + 1, r32, h2);
;                 if (kt + 2 < nt) { *(LAS u32x4*)(buf0 + key0 * KT_ROWB + ch * 16) = a0; *(LAS u32x4*)(buf0 + (key0 + 32) * KT_ROWB + ch * 16) = a1; }
;                 __syncthreads();
	v_mfma_f32_32x32x16_f16 v[16:31], v[36:39], v[176:179], 0
	v_mfma_f32_32x32x16_f16 v[16:31], v[40:43], v[172:175], v[16:31]
	v_mfma_f32_32x32x16_f16 v[16:31], v[44:47], v[168:171], v[16:31]
	s_nop 8
	v_max_i32_e32 v0, 0, v0
	v_max_i32_e32 v1, 0, v1
	v_pk_fma_f32 v[244:245], v[0:1], v[116:117], 0 op_sel_hi:[1,1,0]
	v_max_i32_e32 v2, 0, v2
	v_max_i32_e32 v3, 0, v3
	v_mfma_f32_32x32x16_f16 v[16:31], v[48:51], v[164:167], v[16:31]
	v_pk_fma_f32 v[244:245], v[2:3], v[118:119], v[244:245]
	v_max_i32_e32 v4, 0, v4
	v_max_i32_e32 v5, 0, v5
	v_pk_fma_f32 v[244:245], v[4:5], v[120:121], v[244:245]
	v_max_i32_e32 v6, 0, v6
	v_mfma_f32_32x32x16_f16 v[16:31], v[52:55], v[160:163], v[16:31]
	v_max_i32_e32 v7, 0, v7
	v_pk_fma_f32 v[244:245], v[6:7], v[122:123], v[244:245]
	v_max_i32_e32 v8, 0, v8
	v_max_i32_e32 v9, 0, v9
	v_pk_fma_f32 v[244:245], v[8:9], v[124:125], v[244:245]
	v_mfma_f32_32x32x16_f16 v[16:31], v[56:59], v[156:159], v[16:31]
	v_max_i32_e32 v10, 0, v10
	v_max_i32_e32 v11, 0, v11
	v_pk_fma_f32 v[244:245], v[10:11], v[126:127], v[244:245]
	v_max_i32_e32 v12, 0, v12
	v_max_i32_e32 v13, 0, v13
	v_mfma_f32_32x32x16_f16 v[16:31], v[60:63], v[152:155], v[16:31]
	v_pk_fma_f32 v[244:245], v[12:13], v[128:129], v[244:245]
	v_max_i32_e32 v14, 0, v14
	v_max_i32_e32 v15, 0, v15
	v_pk_fma_f32 v[244:245], v[14:15], v[130:131], v[244:245]
	v_mfma_f32_32x32x16_f16 v[16:31], v[64:67], v[148:151], v[16:31]
	v_add_f32_e32 v246, v244, v245
	v_mov_b32_e32 v247, v246
	v_lshlrev_b32_e32 v248, 2, v32
	s_nop 0
	v_permlane32_swap_b32_e32 v247, v246
	v_add_f32_e32 v247, v247, v246
	s_mov_b64 exec, s[4:5]
	global_store_dword v248, v247, s[8:9] offset:256
	s_mov_b64 exec, -1
	v_mfma_f32_32x32x16_f16 v[0:15], v[84:87], v[176:179], 0
	v_mfma_f32_32x32x16_f16 v[0:15], v[88:91], v[172:175], v[0:15]
	v_mfma_f32_32x32x16_f16 v[0:15], v[92:95], v[168:171], v[0:15]
	s_nop 8
	v_max_i32_e32 v16, 0, v16
	v_max_i32_e32 v17, 0, v17
	v_pk_fma_f32 v[238:239], v[16:17], v[68:69], 0 op_sel_hi:[1,1,0]
	v_max_i32_e32 v18, 0, v18
	v_max_i32_e32 v19, 0, v19
	v_mfma_f32_32x32x16_f16 v[0:15], v[96:99], v[164:167], v[0:15]
	v_pk_fma_f32 v[238:239], v[18:19], v[70:71], v[238:239]
	v_max_i32_e32 v20, 0, v20
	v_max_i32_e32 v21, 0, v21
	v_pk_fma_f32 v[238:239], v[20:21], v[72:73], v[238:239]
	v_max_i32_e32 v22, 0, v22
	v_mfma_f32_32x32x16_f16 v[0:15], v[100:103], v[160:163], v[0:15]
	v_max_i32_e32 v23, 0, v23
	v_pk_fma_f32 v[238:239], v[22:23], v[74:75], v[238:239]
	v_max_i32_e32 v24, 0, v24
	v_max_i32_e32 v25, 0, v25
	v_pk_fma_f32 v[238:239], v[24:25], v[76:77], v[238:239]
	v_mfma_f32_32x32x16_f16 v[0:15], v[104:107], v[156:159], v[0:15]
	v_max_i32_e32 v26, 0, v26
	v_max_i32_e32 v27, 0, v27
	v_pk_fma_f32 v[238:239], v[26:27], v[78:79], v[238:239]
	v_max_i32_e32 v28, 0, v28
	v_max_i32_e32 v29, 0, v29
	v_mfma_f32_32x32x16_f16 v[0:15], v[108:111], v[152:155], v[0:15]
	v_pk_fma_f32 v[238:239], v[28:29], v[80:81], v[238:239]
	v_max_i32_e32 v30, 0, v30
	v_max_i32_e32 v31, 0, v31
	v_pk_fma_f32 v[238:239], v[30:31], v[82:83], v[238:239]
	v_mfma_f32_32x32x16_f16 v[0:15], v[112:115], v[148:151], v[0:15]
	v_add_f32_e32 v240, v238, v239
	v_mov_b32_e32 v241, v240
	v_lshlrev_b32_e32 v242, 2, v32
	s_nop 0
	v_permlane32_swap_b32_e32 v241, v240
	v_add_f32_e32 v241, v241, v240
	s_mov_b64 exec, s[4:5]
	global_store_dword v242, v241, s[6:7] offset:384
	s_mov_b64 exec, -1
	s_nop 11
	v_max_i32_e32 v0, 0, v0
	v_max_i32_e32 v1, 0, v1
	v_pk_fma_f32 v[244:245], v[0:1], v[116:117], 0 op_sel_hi:[1,1,0]
	v_max_i32_e32 v2, 0, v2
	v_max_i32_e32 v3, 0, v3
	v_pk_fma_f32 v[244:245], v[2:3], v[118:119], v[244:245]
	v_max_i32_e32 v4, 0, v4
	v_max_i32_e32 v5, 0, v5
	v_pk_fma_f32 v[244:245], v[4:5], v[120:121], v[244:245]
	v_max_i32_e32 v6, 0, v6
	v_max_i32_e32 v7, 0, v7
	v_pk_fma_f32 v[244:245], v[6:7], v[122:123], v[244:245]
	v_max_i32_e32 v8, 0, v8
	v_max_i32_e32 v9, 0, v9
	v_pk_fma_f32 v[244:245], v[8:9], v[124:125], v[244:245]
	v_max_i32_e32 v10, 0, v10
	v_max_i32_e32 v11, 0, v11
	v_pk_fma_f32 v[244:245], v[10:11], v[126:127], v[244:245]
	v_max_i32_e32 v12, 0, v12
	v_max_i32_e32 v13, 0, v13
	v_pk_fma_f32 v[244:245], v[12:13], v[128:129], v[244:245]
	v_max_i32_e32 v14, 0, v14
	v_max_i32_e32 v15, 0, v15
	v_pk_fma_f32 v[244:245], v[14:15], v[130:131], v[244:245]
	v_add_f32_e32 v246, v244, v245
	v_mov_b32_e32 v247, v246
	v_lshlrev_b32_e32 v248, 2, v32
	s_nop 0
	v_permlane32_swap_b32_e32 v247, v246
	v_add_f32_e32 v247, v247, v246
	s_mov_b64 exec, s[4:5]
	global_store_dword v248, v247, s[8:9] offset:384
	s_mov_b64 exec, -1
	s_andn2_b64 vcc, exec, s[10:11]
	s_cbranch_vccnz .LBB0_1868
	s_waitcnt vmcnt(8)
	ds_write_b128 v209, v[132:135]
	ds_write_b128 v209, v[136:139] offset:8704
	s_branch .LBB0_1868

; #define LAS __attribute__((address_space(3)))
; DI void indexer_tile(const LAS unsigned char* buf, const f16x8 (&af)[2][8], const f32x4 (&wv)[2][4], float* sc0, float* sc1, int kt, int r32, int h2) {
;     ...
;     f16x8 bfr[2][8];
; #pragma unroll
;     for (int sub = 0; sub < 2; ++sub)
; #pragma unroll
;         for (int ks = 0; ks < 8; ++ks) bfr[sub][ks] = *(const LAS f16x8*)(buf + (32 * sub + r32) * KT_ROWB + (16 * ks + 8 * h2) * 2);
;     __builtin_amdgcn_sched_barrier(0);
; #pragma unroll
;     for (int sub = 0; sub < 2; ++sub) {
;         f32x16 c0, c1;
; #pragma unroll
;         for (int i = 0; i < 16; ++i) { c0[i] = 0.f; c1[i] = 0.f; }
; #pragma unroll
;         for (int ks = 0; ks < 8; ++ks) { c0 = __builtin_amdgcn_mfma_f32_32x32x16_f16(af[0][ks], bfr[sub][ks], c0, 0, 0, 0); c1 = __builtin_amdgcn_mfma_f32_32x32x16_f16(af[1][ks], bfr[sub][ks], c1, 0, 0, 0); }
;         f32x2_t a0 = {0.f, 0.f}, a1 = {0.f, 0.f};
; #pragma unroll
;         for (int q = 0; q < 4; ++q)
; #pragma unroll
;             for (int e = 0; e < 4; e += 2) {
;                 const f32x2_t r0 = {relu1(c0[4 * q + e]), relu1(c0[4 * q + e + 1])};
;                 const f32x2_t r1 = {relu1(c1[4 * q + e]), relu1(c1[4 * q + e + 1])};
;                 const f32x2_t w0 = {wv[0][q][e], wv[0][q][e + 1]}, w1 = {wv[1][q][e], wv[1][q][e + 1]};
;                 a0 = __builtin_elementwise_fma(r0, w0, a0); a1 = __builtin_elementwise_fma(r1, w1, a1); }
;         float s0 = a0.x + a0.y, s1 = a1.x + a1.y;
;         s0 += __shfl_xor(s0, 32); s1 += __shfl_xor(s1, 32);
;         if (h2 == 0) { sc0[kt * 64 + 32 * sub + r32] = s0; sc1[kt * 64 + 32 * sub + r32] = s1; }
;     }
.LBB0_1891:
	ds_read_b128 v[0:3], v207
	ds_read_b128 v[210:213], v207 offset:32
	ds_read_b128 v[214:217], v207 offset:64
	ds_read_b128 v[218:221], v207 offset:96
	ds_read_b128 v[222:225], v207 offset:128
	ds_read_b128 v[226:229], v207 offset:160
	ds_read_b128 v[230:233], v207 offset:192
	ds_read_b128 v[234:237], v207 offset:224
	ds_read_b128 v[174:177], v207 offset:8704
	ds_read_b128 v[170:173], v207 offset:8736
	ds_read_b128 v[166:169], v207 offset:8768
	ds_read_b128 v[162:165], v207 offset:8800
	ds_read_b128 v[158:161], v207 offset:8832
	ds_read_b128 v[154:157], v207 offset:8864
	ds_read_b128 v[150:153], v207 offset:8896
	ds_read_b128 v[146:149], v207 offset:8928
	s_waitcnt lgkmcnt(15)
	v_mfma_f32_32x32x16_f16 v[16:31], v[34:37], v[0:3], 0
	s_waitcnt lgkmcnt(14)
	v_mfma_f32_32x32x16_f16 v[16:31], v[38:41], v[210:213], v[16:31]
	s_waitcnt lgkmcnt(13)
	v_mfma_f32_32x32x16_f16 v[16:31], v[42:45], v[214:217], v[16:31]
	s_waitcnt lgkmcnt(12)
	v_mfma_f32_32x32x16_f16 v[16:31], v[46:49], v[218:221], v[16:31]
	s_waitcnt lgkmcnt(11)
	v_mfma_f32_32x32x16_f16 v[16:31], v[50:53], v[222:225], v[16:31]
	s_waitcnt lgkmcnt(10)
	v_mfma_f32_32x32x16_f16 v[16:31], v[54:57], v[226:229], v[16:31]
	s_waitcnt lgkmcnt(9)
	v_mfma_f32_32x32x16_f16 v[16:31], v[58:61], v[230:233], v[16:31]
	s_waitcnt lgkmcnt(8)
	v_mfma_f32_32x32x16_f16 v[16:31], v[62:65], v[234:237], v[16:31]
	v_mfma_f32_32x32x16_f16 v[0:15], v[82:85], v[0:3], 0
	v_mfma_f32_32x32x16_f16 v[0:15], v[86:89], v[210:213], v[0:15]
	v_mfma_f32_32x32x16_f16 v[0:15], v[90:93], v[214:217], v[0:15]
	s_nop 8
	v_max_i32_e32 v16, 0, v16
	v_max_i32_e32 v17, 0, v17
	v_pk_fma_f32 v[238:239], v[16:17], v[66:67], 0 op_sel_hi:[1,1,0]
	v_max_i32_e32 v18, 0, v18
	v_max_i32_e32 v19, 0, v19
	v_mfma_f32_32x32x16_f16 v[0:15], v[94:97], v[218:221], v[0:15]
	v_pk_fma_f32 v[238:239], v[18:19], v[68:69], v[238:239]
	v_max_i32_e32 v20, 0, v20
	v_max_i32_e32 v21, 0, v21
	v_pk_fma_f32 v[238:239], v[20:21], v[70:71], v[238:239]
	v_max_i32_e32 v22, 0, v22
	v_mfma_f32_32x32x16_f16 v[0:15], v[98:101], v[222:225], v[0:15]
	v_max_i32_e32 v23, 0, v23
	v_pk_fma_f32 v[238:239], v[22:23], v[72:73], v[238:239]
	v_max_i32_e32 v24, 0, v24
	v_max_i32_e32 v25, 0, v25
	v_pk_fma_f32 v[238:239], v[24:25], v[74:75], v[238:239]
	v_mfma_f32_32x32x16_f16 v[0:15], v[102:105], v[226:229], v[0:15]
	v_max_i32_e32 v26, 0, v26
	v_max_i32_e32 v27, 0, v27
	v_pk_fma_f32 v[238:239], v[26:27], v[76:77], v[238:239]
	v_max_i32_e32 v28, 0, v28
	v_max_i32_e32 v29, 0, v29
	v_mfma_f32_32x32x16_f16 v[0:15], v[106:109], v[230:233], v[0:15]
	v_pk_fma_f32 v[238:239], v[28:29], v[78:79], v[238:239]
	v_max_i32_e32 v30, 0, v30
	v_max_i32_e32 v31, 0, v31
	v_pk_fma_f32 v[238:239], v[30:31], v[80:81], v[238:239]
	v_mfma_f32_32x32x16_f16 v[0:15], v[110:113], v[234:237], v[0:15]
	v_add_f32_e32 v240, v238, v239
	v_mov_b32_e32 v241, v240
	v_lshlrev_b32_e32 v242, 2, v32
	s_nop 0
	v_permlane32_swap_b32_e32 v241, v240
	v_add_f32_e32 v241, v241, v240
	s_mov_b64 exec, s[4:5]
	global_store_dword v242, v241, s[6:7]
	s_mov_b64 exec, -1
	s_waitcnt lgkmcnt(0)
; DI void indexer_tile(const LAS unsigned char* buf, const f16x8 (&af)[2][8], const f32x4 (&wv)[2][4], float* sc0, float* sc1, int kt, int r32, int h2) {
;     ...
;     for (int sub = 0; sub < 2; ++sub) {
;         f32x16 c0, c1;
; #pragma unroll
;         for (int i = 0; i < 16; ++i) { c0[i] = 0.f; c1[i] = 0.f; }
; #pragma unroll
;         for (int ks = 0; ks < 8; ++ks) { c0 = __builtin_amdgcn_mfma_f32_32x32x16_f16(af[0][ks], bfr[sub][ks], c0, 0, 0, 0); c1 = __builtin_amdgcn_mfma_f32_32x32x16_f16(af[1][ks], bfr[sub][ks], c1, 0, 0, 0); }
;         f32x2_t a0 = {0.f, 0.f}, a1 = {0.f, 0.f};
; #pragma unroll
;         for (int q = 0; q < 4; ++q)
; #pragma unroll
;             for (int e = 0; e < 4; e += 2) {
;                 const f32x2_t r0 = {relu1(c0[4 * q + e]), relu1(c0[4 * q + e + 1])};
;                 const f32x2_t r1 = {relu1(c1[4 * q + e]), relu1(c1[4 * q + e + 1])};
;                 const f32x2_t w0 = {wv[0][q][e], wv[0][q][e + 1]}, w1 = {wv[1][q][e], wv[1][q][e + 1]};
;                 a0 = __builtin_elementwise_fma(r0, w0, a0); a1 = __builtin_elementwise_fma(r1, w1, a1); }
;         float s0 = a0.x + a0.y, s1 = a1.x + a1.y;
;         s0 += __shfl_xor(s0, 32); s1 += __shfl_xor(s1, 32);
;         if (h2 == 0) { sc0[kt * 64 + 32 * sub + r32] = s0; sc1[kt * 64 + 32 * sub + r32] = s1; }
;     }
	v_mfma_f32_32x32x16_f16 v[16:31], v[34:37], v[174:177], 0
	v_mfma_f32_32x32x16_f16 v[16:31], v[38:41], v[170:173], v[16:31]
	v_mfma_f32_32x32x16_f16 v[16:31], v[42:45], v[166:169], v[16:31]
	s_nop 8
	v_max_i32_e32 v0, 0, v0
	v_max_i32_e32 v1, 0, v1
	v_pk_fma_f32 v[244:245], v[0:1], v[114:115], 0 op_sel_hi:[1,1,0]
	v_max_i32_e32 v2, 0, v2
	v_max_i32_e32 v3, 0, v3
	v_mfma_f32_32x32x16_f16 v[16:31], v[46:49], v[162:165], v[16:31]
	v_pk_fma_f32 v[244:245], v[2:3], v[116:117], v[244:245]
	v_max_i32_e32 v4, 0, v4
	v_max_i32_e32 v5, 0, v5
	v_pk_fma_f32 v[244:245], v[4:5], v[118:119], v[244:245]
	v_max_i32_e32 v6, 0, v6
	v_mfma_f32_32x32x16_f16 v[16:31], v[50:53], v[158:161], v[16:31]
	v_max_i32_e32 v7, 0, v7
	v_pk_fma_f32 v[244:245], v[6:7], v[120:121], v[244:245]
	v_max_i32_e32 v8, 0, v8
	v_max_i32_e32 v9, 0, v9
	v_pk_fma_f32 v[244:245], v[8:9], v[122:123], v[244:245]
	v_mfma_f32_32x32x16_f16 v[16:31], v[54:57], v[154:157], v[16:31]
	v_max_i32_e32 v10, 0, v10
	v_max_i32_e32 v11, 0, v11
	v_pk_fma_f32 v[244:245], v[10:11], v[124:125], v[244:245]
	v_max_i32_e32 v12, 0, v12
	v_max_i32_e32 v13, 0, v13
	v_mfma_f32_32x32x16_f16 v[16:31], v[58:61], v[150:153], v[16:31]
	v_pk_fma_f32 v[244:245], v[12:13], v[126:127], v[244:245]
	v_max_i32_e32 v14, 0, v14
	v_max_i32_e32 v15, 0, v15
	v_pk_fma_f32 v[244:245], v[14:15], v[128:129], v[244:245]
	v_mfma_f32_32x32x16_f16 v[16:31], v[62:65], v[146:149], v[16:31]
	v_add_f32_e32 v246, v244, v245
	v_mov_b32_e32 v247, v246
	v_lshlrev_b32_e32 v248, 2, v32
	s_nop 0
	v_permlane32_swap_b32_e32 v247, v246
	v_add_f32_e32 v247, v247, v246
	s_mov_b64 exec, s[4:5]
	global_store_dword v248, v247, s[8:9]
	s_mov_b64 exec, -1
	v_mfma_f32_32x32x16_f16 v[0:15], v[82:85], v[174:177], 0
	v_mfma_f32_32x32x16_f16 v[0:15], v[86:89], v[170:173], v[0:15]
	v_mfma_f32_32x32x16_f16 v[0:15], v[90:93], v[166:169], v[0:15]
	s_nop 8
	v_max_i32_e32 v16, 0, v16
	v_max_i32_e32 v17, 0, v17
	v_pk_fma_f32 v[238:239], v[16:17], v[66:67], 0 op_sel_hi:[1,1,0]
	v_max_i32_e32 v18, 0, v18
	v_max_i32_e32 v19, 0, v19
	v_mfma_f32_32x32x16_f16 v[0:15], v[94:97], v[162:165], v[0:15]
	v_pk_fma_f32 v[238:239], v[18:19], v[68:69], v[238:239]
	v_max_i32_e32 v20, 0, v20
	v_max_i32_e32 v21, 0, v21
	v_pk_fma_f32 v[238:239], v[20:21], v[70:71], v[238:239]
	v_max_i32_e32 v22, 0, v22
	v_mfma_f32_32x32x16_f16 v[0:15], v[98:101], v[158:161], v[0:15]
	v_max_i32_e32 v23, 0, v23
	v_pk_fma_f32 v[238:239], v[22:23], v[72:73], v[238:239]
	v_max_i32_e32 v24, 0, v24
	v_max_i32_e32 v25, 0, v25
	v_pk_fma_f32 v[238:239], v[24:25], v[74:75], v[238:239]
	v_mfma_f32_32x32x16_f16 v[0:15], v[102:105], v[154:157], v[0:15]
	v_max_i32_e32 v26, 0, v26
	v_max_i32_e32 v27, 0, v27
	v_pk_fma_f32 v[238:239], v[26:27], v[76:77], v[238:239]
	v_max_i32_e32 v28, 0, v28
	v_max_i32_e32 v29, 0, v29
	v_mfma_f32_32x32x16_f16 v[0:15], v[106:109], v[150:153], v[0:15]
	v_pk_fma_f32 v[238:239], v[28:29], v[78:79], v[238:239]
	v_max_i32_e32 v30, 0, v30
	v_max_i32_e32 v31, 0, v31
	v_pk_fma_f32 v[238:239], v[30:31], v[80:81], v[238:239]
	v_mfma_f32_32x32x16_f16 v[0:15], v[110:113], v[146:149], v[0:15]
	v_add_f32_e32 v240, v238, v239
	v_mov_b32_e32 v241, v240
	v_lshlrev_b32_e32 v242, 2, v32
	s_nop 0
	v_permlane32_swap_b32_e32 v241, v240
	v_add_f32_e32 v241, v241, v240
	s_mov_b64 exec, s[4:5]
	global_store_dword v242, v241, s[6:7] offset:128
	s_mov_b64 exec, -1
	s_nop 11
	v_max_i32_e32 v0, 0, v0
	v_max_i32_e32 v1, 0, v1
	v_pk_fma_f32 v[244:245], v[0:1], v[114:115], 0 op_sel_hi:[1,1,0]
	v_max_i32_e32 v2, 0, v2
	v_max_i32_e32 v3, 0, v3
	v_pk_fma_f32 v[244:245], v[2:3], v[116:117], v[244:245]
	v_max_i32_e32 v4, 0, v4
	v_max_i32_e32 v5, 0, v5
	v_pk_fma_f32 v[244:245], v[4:5], v[118:119], v[244:245]
	v_max_i32_e32 v6, 0, v6
	v_max_i32_e32 v7, 0, v7
	v_pk_fma_f32 v[244:245], v[6:7], v[120:121], v[244:245]
	v_max_i32_e32 v8, 0, v8
	v_max_i32_e32 v9, 0, v9
	v_pk_fma_f32 v[244:245], v[8:9], v[122:123], v[244:245]
	v_max_i32_e32 v10, 0, v10
	v_max_i32_e32 v11, 0, v11
	v_pk_fma_f32 v[244:245], v[10:11], v[124:125], v[244:245]
	v_max_i32_e32 v12, 0, v12
	v_max_i32_e32 v13, 0, v13
	v_pk_fma_f32 v[244:245], v[12:13], v[126:127], v[244:245]
	v_max_i32_e32 v14, 0, v14
	v_max_i32_e32 v15, 0, v15
	v_pk_fma_f32 v[244:245], v[14:15], v[128:129], v[244:245]
	v_add_f32_e32 v246, v244, v245
	v_mov_b32_e32 v247, v246
	v_lshlrev_b32_e32 v248, 2, v32
	s_nop 0
	v_permlane32_swap_b32_e32 v247, v246
	v_add_f32_e32 v247, v247, v246
	s_mov_b64 exec, s[4:5]
	global_store_dword v248, v247, s[8:9] offset:128
	s_mov_b64 exec, -1
	s_add_i32 s18, s14, -3
	s_cmp_lt_u32 s18, s42
	s_cselect_b64 s[12:13], -1, 0
	s_cmp_ge_u32 s18, s42
	s_cbranch_scc1 .LBB0_1897
	s_waitcnt vmcnt(8)
	ds_write_b128 v209, v[134:137] offset:17408
	ds_write_b128 v209, v[142:145] offset:26112

; #define LAS __attribute__((address_space(3)))
; DI void indexer_tile(const LAS unsigned char* buf, const f16x8 (&af)[2][8], const f32x4 (&wv)[2][4], float* sc0, float* sc1, int kt, int r32, int h2) {
;     ...
;     f16x8 bfr[2][8];
; #pragma unroll
;     for (int sub = 0; sub < 2; ++sub)
; #pragma unroll
;         for (int ks = 0; ks < 8; ++ks) bfr[sub][ks] = *(const LAS f16x8*)(buf + (32 * sub + r32) * KT_ROWB + (16 * ks + 8 * h2) * 2);
;     __builtin_amdgcn_sched_barrier(0);
; #pragma unroll
;     for (int sub = 0; sub < 2; ++sub) {
;         f32x16 c0, c1;
; #pragma unroll
;         for (int i = 0; i < 16; ++i) { c0[i] = 0.f; c1[i] = 0.f; }
; #pragma unroll
;         for (int ks = 0; ks < 8; ++ks) { c0 = __builtin_amdgcn_mfma_f32_32x32x16_f16(af[0][ks], bfr[sub][ks], c0, 0, 0, 0); c1 = __builtin_amdgcn_mfma_f32_32x32x16_f16(af[1][ks], bfr[sub][ks], c1, 0, 0, 0); }
;         f32x2_t a0 = {0.f, 0.f}, a1 = {0.f, 0.f};
; #pragma unroll
;         for (int q = 0; q < 4; ++q)
; #pragma unroll
;             for (int e = 0; e < 4; e += 2) {
;                 const f32x2_t r0 = {relu1(c0[4 * q + e]), relu1(c0[4 * q + e + 1])};
;                 const f32x2_t r1 = {relu1(c1[4 * q + e]), relu1(c1[4 * q + e + 1])};
;                 const f32x2_t w0 = {wv[0][q][e], wv[0][q][e + 1]}, w1 = {wv[1][q][e], wv[1][q][e + 1]};
;                 a0 = __builtin_elementwise_fma(r0, w0, a0); a1 = __builtin_elementwise_fma(r1, w1, a1); }
;         float s0 = a0.x + a0.y, s1 = a1.x + a1.y;
;         s0 += __shfl_xor(s0, 32); s1 += __shfl_xor(s1, 32);
;         if (h2 == 0) { sc0[kt * 64 + 32 * sub + r32] = s0; sc1[kt * 64 + 32 * sub + r32] = s1; }
;     }
.LBB0_1900:
	ds_read_b128 v[0:3], v207 offset:17408
	ds_read_b128 v[210:213], v207 offset:17440
	ds_read_b128 v[214:217], v207 offset:17472
	ds_read_b128 v[218:221], v207 offset:17504
	ds_read_b128 v[222:225], v207 offset:17536
	ds_read_b128 v[226:229], v207 offset:17568
	ds_read_b128 v[230:233], v207 offset:17600
	ds_read_b128 v[234:237], v207 offset:17632
	ds_read_b128 v[174:177], v207 offset:26112
	ds_read_b128 v[170:173], v207 offset:26144
	ds_read_b128 v[166:169], v207 offset:26176
	ds_read_b128 v[162:165], v207 offset:26208
	ds_read_b128 v[158:161], v207 offset:26240
	ds_read_b128 v[154:157], v207 offset:26272
	ds_read_b128 v[150:153], v207 offset:26304
	ds_read_b128 v[146:149], v207 offset:26336
	s_waitcnt lgkmcnt(15)
	v_mfma_f32_32x32x16_f16 v[16:31], v[34:37], v[0:3], 0
	s_waitcnt lgkmcnt(14)
	v_mfma_f32_32x32x16_f16 v[16:31], v[38:41], v[210:213], v[16:31]
	s_waitcnt lgkmcnt(13)
	v_mfma_f32_32x32x16_f16 v[16:31], v[42:45], v[214:217], v[16:31]
	s_waitcnt lgkmcnt(12)
	v_mfma_f32_32x32x16_f16 v[16:31], v[46:49], v[218:221], v[16:31]
	s_waitcnt lgkmcnt(11)
	v_mfma_f32_32x32x16_f16 v[16:31], v[50:53], v[222:225], v[16:31]
	s_waitcnt lgkmcnt(10)
	v_mfma_f32_32x32x16_f16 v[16:31], v[54:57], v[226:229], v[16:31]
	s_waitcnt lgkmcnt(9)
	v_mfma_f32_32x32x16_f16 v[16:31], v[58:61], v[230:233], v[16:31]
	s_waitcnt lgkmcnt(8)
	v_mfma_f32_32x32x16_f16 v[16:31], v[62:65], v[234:237], v[16:31]
	v_mfma_f32_32x32x16_f16 v[0:15], v[82:85], v[0:3], 0
	v_mfma_f32_32x32x16_f16 v[0:15], v[86:89], v[210:213], v[0:15]
	v_mfma_f32_32x32x16_f16 v[0:15], v[90:93], v[214:217], v[0:15]
	s_nop 8
	v_max_i32_e32 v16, 0, v16
	v_max_i32_e32 v17, 0, v17
	v_pk_fma_f32 v[238:239], v[16:17], v[66:67], 0 op_sel_hi:[1,1,0]
	v_max_i32_e32 v18, 0, v18
	v_max_i32_e32 v19, 0, v19
	v_mfma_f32_32x32x16_f16 v[0:15], v[94:97], v[218:221], v[0:15]
	v_pk_fma_f32 v[238:239], v[18:19], v[68:69], v[238:239]
	v_max_i32_e32 v20, 0, v20
	v_max_i32_e32 v21, 0, v21
	v_pk_fma_f32 v[238:239], v[20:21], v[70:71], v[238:239]
	v_max_i32_e32 v22, 0, v22
	v_mfma_f32_32x32x16_f16 v[0:15], v[98:101], v[222:225], v[0:15]
	v_max_i32_e32 v23, 0, v23
	v_pk_fma_f32 v[238:239], v[22:23], v[72:73], v[238:239]
	v_max_i32_e32 v24, 0, v24
	v_max_i32_e32 v25, 0, v25
	v_pk_fma_f32 v[238:239], v[24:25], v[74:75], v[238:239]
	v_mfma_f32_32x32x16_f16 v[0:15], v[102:105], v[226:229], v[0:15]
	v_max_i32_e32 v26, 0, v26
	v_max_i32_e32 v27, 0, v27
	v_pk_fma_f32 v[238:239], v[26:27], v[76:77], v[238:239]
	v_max_i32_e32 v28, 0, v28
	v_max_i32_e32 v29, 0, v29
	v_mfma_f32_32x32x16_f16 v[0:15], v[106:109], v[230:233], v[0:15]
	v_pk_fma_f32 v[238:239], v[28:29], v[78:79], v[238:239]
	v_max_i32_e32 v30, 0, v30
	v_max_i32_e32 v31, 0, v31
	v_pk_fma_f32 v[238:239], v[30:31], v[80:81], v[238:239]
	v_mfma_f32_32x32x16_f16 v[0:15], v[110:113], v[234:237], v[0:15]
	v_add_f32_e32 v240, v238, v239
	v_mov_b32_e32 v241, v240
	v_lshlrev_b32_e32 v242, 2, v32
	s_nop 0
	v_permlane32_swap_b32_e32 v241, v240
	v_add_f32_e32 v241, v241, v240
	s_mov_b64 exec, s[4:5]
	global_store_dword v242, v241, s[6:7] offset:256
	s_mov_b64 exec, -1
	s_waitcnt lgkmcnt(0)
; #define LAS __attribute__((address_space(3)))
; DI void indexer_tile(const LAS unsigned char* buf, const f16x8 (&af)[2][8], const f32x4 (&wv)[2][4], float* sc0, float* sc1, int kt, int r32, int h2) {
;     ...
;     for (int sub = 0; sub < 2; ++sub) {
;         f32x16 c0, c1;
; #pragma unroll
;         for (int i = 0; i < 16; ++i) { c0[i] = 0.f; c1[i] = 0.f; }
; #pragma unroll
;         for (int ks = 0; ks < 8; ++ks) { c0 = __builtin_amdgcn_mfma_f32_32x32x16_f16(af[0][ks], bfr[sub][ks], c0, 0, 0, 0); c1 = __builtin_amdgcn_mfma_f32_32x32x16_f16(af[1][ks], bfr[sub][ks], c1, 0, 0, 0); }
;         f32x2_t a0 = {0.f, 0.f}, a1 = {0.f, 0.f};
; #pragma unroll
;         for (int q = 0; q < 4; ++q)
; #pragma unroll
;             for (int e = 0; e < 4; e += 2) {
;                 const f32x2_t r0 = {relu1(c0[4 * q + e]), relu1(c0[4 * q + e + 1])};
;                 const f32x2_t r1 = {relu1(c1[4 * q + e]), relu1(c1[4 * q + e + 1])};
;                 const f32x2_t w0 = {wv[0][q][e], wv[0][q][e + 1]}, w1 = {wv[1][q][e], wv[1][q][e + 1]};
;                 a0 = __builtin_elementwise_fma(r0, w0, a0); a1 = __builtin_elementwise_fma(r1, w1, a1); }
;         float s0 = a0.x + a0.y, s1 = a1.x + a1.y;
;         s0 += __shfl_xor(s0, 32); s1 += __shfl_xor(s1, 32);
;         if (h2 == 0) { sc0[kt * 64 + 32 * sub + r32] = s0; sc1[kt * 64 + 32 * sub + r32] = s1; }
;     }
; DI void indexer_phase(const unsigned short* QI, const unsigned short* KI16, const float* WI, float* SC, LAS unsigned char* lds, int tid, int bid, int G) {
;     ...
;                 if (kt + 1 >= nt) break;
;                 if (kt + 3 < nt) { const unsigned short* p = src + (size_t)(kt + 3) * 64 * 128; b0 = *(const u32x4*)p; b1 = *(const u32x4*)(p + 32 * 128); }
;                 indexer_tile(buf1, af, wv, sc0, sc1, kt + 1, r32, h2);
;                 if (kt + 2 < nt) { *(LAS u32x4*)(buf0 + key0 * KT_ROWB + ch * 16) = a0; *(LAS u32x4*)(buf0 + (key0 + 32) * KT_ROWB + ch * 16) = a1; }
;                 __syncthreads();
	v_mfma_f32_32x32x16_f16 v[16:31], v[34:37], v[174:177], 0
	v_mfma_f32_32x32x16_f16 v[16:31], v[38:41], v[170:173], v[16:31]
	v_mfma_f32_32x32x16_f16 v[16:31], v[42:45], v[166:169], v[16:31]
	s_nop 8
	v_max_i32_e32 v0, 0, v0
	v_max_i32_e32 v1, 0, v1
	v_pk_fma_f32 v[244:245], v[0:1], v[114:115], 0 op_sel_hi:[1,1,0]
	v_max_i32_e32 v2, 0, v2
	v_max_i32_e32 v3, 0, v3
	v_mfma_f32_32x32x16_f16 v[16:31], v[46:49], v[162:165], v[16:31]
	v_pk_fma_f32 v[244:245], v[2:3], v[116:117], v[244:245]
	v_max_i32_e32 v4, 0, v4
	v_max_i32_e32 v5, 0, v5
	v_pk_fma_f32 v[244:245], v[4:5], v[118:119], v[244:245]
	v_max_i32_e32 v6, 0, v6
	v_mfma_f32_32x32x16_f16 v[16:31], v[50:53], v[158:161], v[16:31]
	v_max_i32_e32 v7, 0, v7
	v_pk_fma_f32 v[244:245], v[6:7], v[120:121], v[244:245]
	v_max_i32_e32 v8, 0, v8
	v_max_i32_e32 v9, 0, v9
	v_pk_fma_f32 v[244:245], v[8:9], v[122:123], v[244:245]
	v_mfma_f32_32x32x16_f16 v[16:31], v[54:57], v[154:157], v[16:31]
	v_max_i32_e32 v10, 0, v10
	v_max_i32_e32 v11, 0, v11
	v_pk_fma_f32 v[244:245], v[10:11], v[124:125], v[244:245]
	v_max_i32_e32 v12, 0, v12
	v_max_i32_e32 v13, 0, v13
	v_mfma_f32_32x32x16_f16 v[16:31], v[58:61], v[150:153], v[16:31]
	v_pk_fma_f32 v[244:245], v[12:13], v[126:127], v[244:245]
	v_max_i32_e32 v14, 0, v14
	v_max_i32_e32 v15, 0, v15
	v_pk_fma_f32 v[244:245], v[14:15], v[128:129], v[244:245]
	v_mfma_f32_32x32x16_f16 v[16:31], v[62:65], v[146:149], v[16:31]
	v_add_f32_e32 v246, v244, v245
	v_mov_b32_e32 v247, v246
	v_lshlrev_b32_e32 v248, 2, v32
	s_nop 0
	v_permlane32_swap_b32_e32 v247, v246
	v_add_f32_e32 v247, v247, v246
	s_mov_b64 exec, s[4:5]
	global_store_dword v248, v247, s[8:9] offset:256
	s_mov_b64 exec, -1
	v_mfma_f32_32x32x16_f16 v[0:15], v[82:85], v[174:177], 0
	v_mfma_f32_32x32x16_f16 v[0:15], v[86:89], v[170:173], v[0:15]
	v_mfma_f32_32x32x16_f16 v[0:15], v[90:93], v[166:169], v[0:15]
	s_nop 8
	v_max_i32_e32 v16, 0, v16
	v_max_i32_e32 v17, 0, v17
	v_pk_fma_f32 v[238:239], v[16:17], v[66:67], 0 op_sel_hi:[1,1,0]
	v_max_i32_e32 v18, 0, v18
	v_max_i32_e32 v19, 0, v19
	v_mfma_f32_32x32x16_f16 v[0:15], v[94:97], v[162:165], v[0:15]
	v_pk_fma_f32 v[238:239], v[18:19], v[68:69], v[238:239]
	v_max_i32_e32 v20, 0, v20
	v_max_i32_e32 v21, 0, v21
	v_pk_fma_f32 v[238:239], v[20:21], v[70:71], v[238:239]
	v_max_i32_e32 v22, 0, v22
	v_mfma_f32_32x32x16_f16 v[0:15], v[98:101], v[158:161], v[0:15]
	v_max_i32_e32 v23, 0, v23
	v_pk_fma_f32 v[238:239], v[22:23], v[72:73], v[238:239]
	v_max_i32_e32 v24, 0, v24
	v_max_i32_e32 v25, 0, v25
	v_pk_fma_f32 v[238:239], v[24:25], v[74:75], v[238:239]
	v_mfma_f32_32x32x16_f16 v[0:15], v[102:105], v[154:157], v[0:15]
	v_max_i32_e32 v26, 0, v26
	v_max_i32_e32 v27, 0, v27
	v_pk_fma_f32 v[238:239], v[26:27], v[76:77], v[238:239]
	v_max_i32_e32 v28, 0, v28
	v_max_i32_e32 v29, 0, v29
	v_mfma_f32_32x32x16_f16 v[0:15], v[106:109], v[150:153], v[0:15]
	v_pk_fma_f32 v[238:239], v[28:29], v[78:79], v[238:239]
	v_max_i32_e32 v30, 0, v30
	v_max_i32_e32 v31, 0, v31
	v_pk_fma_f32 v[238:239], v[30:31], v[80:81], v[238:239]
	v_mfma_f32_32x32x16_f16 v[0:15], v[110:113], v[146:149], v[0:15]
	v_add_f32_e32 v240, v238, v239
	v_mov_b32_e32 v241, v240
	v_lshlrev_b32_e32 v242, 2, v32
	s_nop 0
	v_permlane32_swap_b32_e32 v241, v240
	v_add_f32_e32 v241, v241, v240
	s_mov_b64 exec, s[4:5]
	global_store_dword v242, v241, s[6:7] offset:384
	s_mov_b64 exec, -1
	s_nop 11
	v_max_i32_e32 v0, 0, v0
	v_max_i32_e32 v1, 0, v1
	v_pk_fma_f32 v[244:245], v[0:1], v[114:115], 0 op_sel_hi:[1,1,0]
	v_max_i32_e32 v2, 0, v2
	v_max_i32_e32 v3, 0, v3
	v_pk_fma_f32 v[244:245], v[2:3], v[116:117], v[244:245]
	v_max_i32_e32 v4, 0, v4
	v_max_i32_e32 v5, 0, v5
	v_pk_fma_f32 v[244:245], v[4:5], v[118:119], v[244:245]
	v_max_i32_e32 v6, 0, v6
	v_max_i32_e32 v7, 0, v7
	v_pk_fma_f32 v[244:245], v[6:7], v[120:121], v[244:245]
	v_max_i32_e32 v8, 0, v8
	v_max_i32_e32 v9, 0, v9
	v_pk_fma_f32 v[244:245], v[8:9], v[122:123], v[244:245]
	v_max_i32_e32 v10, 0, v10
	v_max_i32_e32 v11, 0, v11
	v_pk_fma_f32 v[244:245], v[10:11], v[124:125], v[244:245]
	v_max_i32_e32 v12, 0, v12
	v_max_i32_e32 v13, 0, v13
	v_pk_fma_f32 v[244:245], v[12:13], v[126:127], v[244:245]
	v_max_i32_e32 v14, 0, v14
	v_max_i32_e32 v15, 0, v15
	v_pk_fma_f32 v[244:245], v[14:15], v[128:129], v[244:245]
	v_add_f32_e32 v246, v244, v245
	v_mov_b32_e32 v247, v246
	v_lshlrev_b32_e32 v248, 2, v32
	s_nop 0
	v_permlane32_swap_b32_e32 v247, v246
	v_add_f32_e32 v247, v247, v246
	s_mov_b64 exec, s[4:5]
	global_store_dword v248, v247, s[8:9] offset:384
	s_mov_b64 exec, -1
	s_andn2_b64 vcc, exec, s[10:11]
	s_cbranch_vccnz .LBB0_1888
	s_waitcnt vmcnt(8)
	ds_write_b128 v209, v[130:133]
	ds_write_b128 v209, v[138:141] offset:8704
	s_branch .LBB0_1888
